# batched conv halo loads + batched NA bias LDS reads (latency de-serialisation)
# speedup vs baseline: 1.0192x; 1.0192x over previous
; __device__ __forceinline__ int opaque_tid() { int t = threadIdx.x; asm volatile("" : "+v"(t)); return t; }
; #define LAS __attribute__((address_space(3)))
; __device__ __forceinline__ void conv_tile(const Params& p, int l, int item, const bf16* PROJ, bf16* CV, LAS float* sl) {
;     const int tid = opaque_tid(), lane = tid & 63, wave = __builtin_amdgcn_readfirstlane(tid >> 6), c = tid;
;     const int m0 = item * 32, b = m0 / SEQ, s0 = m0 % SEQ;
;     LAS float* part = sl; LAS float* stat = sl + 512;
;     float u[62];
; #pragma unroll
;     for (int rr = 0; rr < 62; ++rr) { const int sq = s0 - 15 + rr; const bool ok = sq >= 0 && sq < SEQ; const bf16* pr = PROJ + (size_t)(b * SEQ + (ok ? sq : s0)) * NIN;
;         const float a = bf2f(pr[PB_A + c]), g = bf2f(pr[PB_G + c]); u[rr] = ok ? a / (1.0f + __expf(-g)) : 0.f; }
.LBB0_299:
	v_readlane_b32 s1, v252, 60
	v_readlane_b32 s12, v254, 62
	s_or_b32 s0, s0, s1
	v_readlane_b32 s13, v254, 63
	s_mov_b32 s9, s13
	s_lshl_b32 s8, s0, 5
	v_readlane_b32 s14, v255, 0
	v_readlane_b32 s15, v255, 1
	v_readlane_b32 s16, v255, 2
	v_readlane_b32 s17, v255, 3
	v_readlane_b32 s18, v255, 4
	v_readlane_b32 s19, v255, 5
	v_readlane_b32 s20, v255, 6
	v_readlane_b32 s21, v255, 7
	v_readlane_b32 s22, v255, 8
	v_readlane_b32 s23, v255, 9
	v_readlane_b32 s24, v255, 10
	v_readlane_b32 s25, v255, 11
	v_readlane_b32 s26, v255, 12
	v_readlane_b32 s27, v255, 13
	s_mov_b64 s[12:13], s[8:9]
	v_writelane_b32 v254, s12, 62
	v_mov_b32_e32 v2, v188
	s_and_b32 s1, s8, 0xfe0
	v_writelane_b32 v255, s14, 0
	v_writelane_b32 v255, s15, 1
	v_writelane_b32 v255, s16, 2
	v_writelane_b32 v255, s17, 3
	v_writelane_b32 v255, s18, 4
	v_writelane_b32 v255, s19, 5
	v_writelane_b32 v255, s20, 6
	v_writelane_b32 v255, s21, 7
	v_writelane_b32 v255, s22, 8
	v_writelane_b32 v255, s23, 9
	v_writelane_b32 v255, s24, 10
	v_writelane_b32 v255, s25, 11
	v_writelane_b32 v254, s13, 63
	v_writelane_b32 v255, s26, 12
	v_writelane_b32 v255, s27, 13
	v_readlane_b32 s12, v254, 6
	s_and_b32 s0, s8, 0x7ffff000
	s_add_i32 s8, s1, -15
	v_ashrrev_i32_e32 v3, 31, v2
	v_readlane_b32 s13, v254, 7
	v_mov_b32_e32 v26, 0
	s_cmpk_gt_u32 s8, 0xfff
	v_lshl_add_u64 v[4:5], v[2:3], 1, s[12:13]
	v_mov_b32_e32 v28, 0
	v_add_co_u32_e32 v164, vcc, 0xe00, v4
	s_nop 1
	v_addc_co_u32_e32 v165, vcc, 0, v5, vcc
	s_add_i32 s8, s1, -15
	s_cmpk_gt_u32 s8, 0xfff
	s_cselect_b32 s8, s1, s8
	s_or_b32 s8, s8, s0
	v_mad_u64_u32 v[6:7], s[8:9], s8, v195, v[164:165]
	global_load_ushort v208, v[6:7], off offset:512
	global_load_ushort v209, v[6:7], off offset:-512
	s_add_i32 s8, s1, -14
	s_cmpk_gt_u32 s8, 0xfff
	s_cselect_b32 s8, s1, s8
	s_or_b32 s8, s8, s0
	v_mad_u64_u32 v[6:7], s[8:9], s8, v195, v[164:165]
	global_load_ushort v210, v[6:7], off offset:512
	global_load_ushort v211, v[6:7], off offset:-512
	s_add_i32 s8, s1, -13
	s_cmpk_gt_u32 s8, 0xfff
	s_cselect_b32 s8, s1, s8
	s_or_b32 s8, s8, s0
	v_mad_u64_u32 v[6:7], s[8:9], s8, v195, v[164:165]
	global_load_ushort v212, v[6:7], off offset:512
	global_load_ushort v213, v[6:7], off offset:-512
	s_add_i32 s8, s1, -12
	s_cmpk_gt_u32 s8, 0xfff
	s_cselect_b32 s8, s1, s8
	s_or_b32 s8, s8, s0
	v_mad_u64_u32 v[6:7], s[8:9], s8, v195, v[164:165]
	global_load_ushort v214, v[6:7], off offset:512
	global_load_ushort v215, v[6:7], off offset:-512
	s_add_i32 s8, s1, -11
	s_cmpk_gt_u32 s8, 0xfff
	s_cselect_b32 s8, s1, s8
	s_or_b32 s8, s8, s0
	v_mad_u64_u32 v[6:7], s[8:9], s8, v195, v[164:165]
	global_load_ushort v216, v[6:7], off offset:512
	global_load_ushort v217, v[6:7], off offset:-512
	s_add_i32 s8, s1, -10
	s_cmpk_gt_u32 s8, 0xfff
	s_cselect_b32 s8, s1, s8
	s_or_b32 s8, s8, s0
	v_mad_u64_u32 v[6:7], s[8:9], s8, v195, v[164:165]
	global_load_ushort v218, v[6:7], off offset:512
	global_load_ushort v219, v[6:7], off offset:-512
	s_add_i32 s8, s1, -9
	s_cmpk_gt_u32 s8, 0xfff
	s_cselect_b32 s8, s1, s8
	s_or_b32 s8, s8, s0
	v_mad_u64_u32 v[6:7], s[8:9], s8, v195, v[164:165]
	global_load_ushort v220, v[6:7], off offset:512
	global_load_ushort v221, v[6:7], off offset:-512
	s_add_i32 s8, s1, -8
	s_cmpk_gt_u32 s8, 0xfff
	s_cselect_b32 s8, s1, s8
	s_or_b32 s8, s8, s0
	v_mad_u64_u32 v[6:7], s[8:9], s8, v195, v[164:165]
	global_load_ushort v222, v[6:7], off offset:512
	global_load_ushort v223, v[6:7], off offset:-512
	s_add_i32 s8, s1, -7
	s_cmpk_gt_u32 s8, 0xfff
	s_cselect_b32 s8, s1, s8
	s_or_b32 s8, s8, s0
	v_mad_u64_u32 v[6:7], s[8:9], s8, v195, v[164:165]
	global_load_ushort v224, v[6:7], off offset:512
	global_load_ushort v225, v[6:7], off offset:-512
	s_add_i32 s8, s1, -6
	s_cmpk_gt_u32 s8, 0xfff
	s_cselect_b32 s8, s1, s8
	s_or_b32 s8, s8, s0
	v_mad_u64_u32 v[6:7], s[8:9], s8, v195, v[164:165]
	global_load_ushort v226, v[6:7], off offset:512
	global_load_ushort v227, v[6:7], off offset:-512
	s_add_i32 s8, s1, -5
	s_cmpk_gt_u32 s8, 0xfff
	s_cselect_b32 s8, s1, s8
	s_or_b32 s8, s8, s0
	v_mad_u64_u32 v[6:7], s[8:9], s8, v195, v[164:165]
	global_load_ushort v228, v[6:7], off offset:512
	global_load_ushort v229, v[6:7], off offset:-512
	s_add_i32 s8, s1, -4
	s_cmpk_gt_u32 s8, 0xfff
	s_cselect_b32 s8, s1, s8
	s_or_b32 s8, s8, s0
	v_mad_u64_u32 v[6:7], s[8:9], s8, v195, v[164:165]
	global_load_ushort v230, v[6:7], off offset:512
	global_load_ushort v231, v[6:7], off offset:-512
	s_add_i32 s8, s1, -3
	s_cmpk_gt_u32 s8, 0xfff
	s_cselect_b32 s8, s1, s8
	s_or_b32 s8, s8, s0
	v_mad_u64_u32 v[6:7], s[8:9], s8, v195, v[164:165]
	global_load_ushort v232, v[6:7], off offset:512
	global_load_ushort v233, v[6:7], off offset:-512
	s_add_i32 s8, s1, -2
	s_cmpk_gt_u32 s8, 0xfff
	s_cselect_b32 s8, s1, s8
	s_or_b32 s8, s8, s0
	v_mad_u64_u32 v[6:7], s[8:9], s8, v195, v[164:165]
	global_load_ushort v234, v[6:7], off offset:512
	global_load_ushort v235, v[6:7], off offset:-512
	s_add_i32 s8, s1, -1
	s_cmpk_gt_u32 s8, 0xfff
	s_cselect_b32 s8, s1, s8
	s_or_b32 s8, s8, s0
	v_mad_u64_u32 v[6:7], s[8:9], s8, v195, v[164:165]
	global_load_ushort v236, v[6:7], off offset:512
	global_load_ushort v237, v[6:7], off offset:-512
	s_add_i32 s8, s1, 32
	s_cmpk_gt_u32 s8, 0xfff
	s_cselect_b32 s8, s1, s8
	s_or_b32 s8, s8, s0
	v_mad_u64_u32 v[6:7], s[8:9], s8, v195, v[164:165]
	global_load_ushort v238, v[6:7], off offset:512
	global_load_ushort v239, v[6:7], off offset:-512
	s_add_i32 s8, s1, 33
	s_cmpk_gt_u32 s8, 0xfff
	s_cselect_b32 s8, s1, s8
	s_or_b32 s8, s8, s0
	v_mad_u64_u32 v[6:7], s[8:9], s8, v195, v[164:165]
	global_load_ushort v240, v[6:7], off offset:512
	global_load_ushort v241, v[6:7], off offset:-512
; __device__ __forceinline__ void conv_tile(const Params& p, int l, int item, const bf16* PROJ, bf16* CV, LAS float* sl) {
;     ...
;     for (int rr = 0; rr < 62; ++rr) { const int sq = s0 - 15 + rr; const bool ok = sq >= 0 && sq < SEQ; const bf16* pr = PROJ + (size_t)(b * SEQ + (ok ? sq : s0)) * NIN;
;         const float a = bf2f(pr[PB_A + c]), g = bf2f(pr[PB_G + c]); u[rr] = ok ? a / (1.0f + __expf(-g)) : 0.f; }
	s_add_i32 s8, s1, 34
	s_cmpk_gt_u32 s8, 0xfff
	s_cselect_b32 s8, s1, s8
	s_or_b32 s8, s8, s0
	v_mad_u64_u32 v[6:7], s[8:9], s8, v195, v[164:165]
	global_load_ushort v242, v[6:7], off offset:512
	global_load_ushort v243, v[6:7], off offset:-512
	s_add_i32 s8, s1, 35
	s_cmpk_gt_u32 s8, 0xfff
	s_cselect_b32 s8, s1, s8
	s_or_b32 s8, s8, s0
	v_mad_u64_u32 v[6:7], s[8:9], s8, v195, v[164:165]
	global_load_ushort v244, v[6:7], off offset:512
	global_load_ushort v245, v[6:7], off offset:-512
	s_add_i32 s8, s1, 36
	s_cmpk_gt_u32 s8, 0xfff
	s_cselect_b32 s8, s1, s8
	s_or_b32 s8, s8, s0
	v_mad_u64_u32 v[6:7], s[8:9], s8, v195, v[164:165]
	global_load_ushort v246, v[6:7], off offset:512
	global_load_ushort v247, v[6:7], off offset:-512
	s_add_i32 s8, s1, 37
	s_cmpk_gt_u32 s8, 0xfff
	s_cselect_b32 s8, s1, s8
	s_or_b32 s8, s8, s0
	v_mad_u64_u32 v[6:7], s[8:9], s8, v195, v[164:165]
	global_load_ushort v248, v[6:7], off offset:512
	global_load_ushort v249, v[6:7], off offset:-512
	s_add_i32 s8, s1, 38
	s_cmpk_gt_u32 s8, 0xfff
	s_cselect_b32 s8, s1, s8
	s_or_b32 s8, s8, s0
	v_mad_u64_u32 v[6:7], s[8:9], s8, v195, v[164:165]
	global_load_ushort v141, v[6:7], off offset:512
	global_load_ushort v142, v[6:7], off offset:-512
	s_add_i32 s8, s1, 39
	s_cmpk_gt_u32 s8, 0xfff
	s_cselect_b32 s8, s1, s8
	s_or_b32 s8, s8, s0
	v_mad_u64_u32 v[6:7], s[8:9], s8, v195, v[164:165]
	global_load_ushort v143, v[6:7], off offset:512
	global_load_ushort v144, v[6:7], off offset:-512
	s_add_i32 s8, s1, 40
	s_cmpk_gt_u32 s8, 0xfff
	s_cselect_b32 s8, s1, s8
	s_or_b32 s8, s8, s0
	v_mad_u64_u32 v[6:7], s[8:9], s8, v195, v[164:165]
	global_load_ushort v145, v[6:7], off offset:512
	global_load_ushort v146, v[6:7], off offset:-512
	s_add_i32 s8, s1, 41
	s_cmpk_gt_u32 s8, 0xfff
	s_cselect_b32 s8, s1, s8
	s_or_b32 s8, s8, s0
	v_mad_u64_u32 v[6:7], s[8:9], s8, v195, v[164:165]
	global_load_ushort v147, v[6:7], off offset:512
	global_load_ushort v148, v[6:7], off offset:-512
	s_add_i32 s8, s1, 42
	s_cmpk_gt_u32 s8, 0xfff
	s_cselect_b32 s8, s1, s8
	s_or_b32 s8, s8, s0
	v_mad_u64_u32 v[6:7], s[8:9], s8, v195, v[164:165]
	global_load_ushort v149, v[6:7], off offset:512
	global_load_ushort v150, v[6:7], off offset:-512
	s_add_i32 s8, s1, 43
	s_cmpk_gt_u32 s8, 0xfff
	s_cselect_b32 s8, s1, s8
	s_or_b32 s8, s8, s0
	v_mad_u64_u32 v[6:7], s[8:9], s8, v195, v[164:165]
	global_load_ushort v151, v[6:7], off offset:512
	global_load_ushort v152, v[6:7], off offset:-512
	s_add_i32 s8, s1, 44
	s_cmpk_gt_u32 s8, 0xfff
	s_cselect_b32 s8, s1, s8
	s_or_b32 s8, s8, s0
	v_mad_u64_u32 v[6:7], s[8:9], s8, v195, v[164:165]
	global_load_ushort v153, v[6:7], off offset:512
	global_load_ushort v156, v[6:7], off offset:-512
	s_add_i32 s8, s1, 45
	s_cmpk_gt_u32 s8, 0xfff
	s_cselect_b32 s8, s1, s8
	s_or_b32 s8, s8, s0
	v_mad_u64_u32 v[6:7], s[8:9], s8, v195, v[164:165]
	global_load_ushort v157, v[6:7], off offset:512
	global_load_ushort v158, v[6:7], off offset:-512
	s_add_i32 s8, s1, 46
	s_cmpk_gt_u32 s8, 0xfff
	s_cselect_b32 s8, s1, s8
	s_or_b32 s8, s8, s0
	v_mad_u64_u32 v[6:7], s[8:9], s8, v195, v[164:165]
	global_load_ushort v159, v[6:7], off offset:512
	global_load_ushort v160, v[6:7], off offset:-512
	s_waitcnt vmcnt(0)
	s_add_i32 s8, s1, -15
	s_cmpk_gt_u32 s8, 0xfff
	s_cbranch_scc1 .LBB0_301
	v_lshlrev_b32_e32 v7, 16, v208
	v_mul_f32_e32 v7, 0xbfb8aa3b, v7
	v_exp_f32_e32 v7, v7
	v_lshlrev_b32_e32 v6, 16, v209
	v_add_f32_e32 v7, 1.0, v7
	v_div_scale_f32 v8, s[8:9], v7, v7, v6
	v_rcp_f32_e32 v9, v8
	v_div_scale_f32 v13, vcc, v6, v7, v6
	v_fma_f32 v14, -v8, v9, 1.0
	v_fmac_f32_e32 v9, v14, v9
	v_mul_f32_e32 v14, v13, v9
	v_fma_f32 v15, -v8, v14, v13
	v_fmac_f32_e32 v14, v15, v9
	v_fma_f32 v8, -v8, v14, v13
	v_div_fmas_f32 v8, v8, v9, v14
	v_div_fixup_f32 v28, v8, v7, v6
.LBB0_301:
	s_add_i32 s8, s1, -14
	s_cmpk_gt_u32 s8, 0xfff
	s_cbranch_scc1 .LBB0_303
	v_lshlrev_b32_e32 v7, 16, v210
	v_mul_f32_e32 v7, 0xbfb8aa3b, v7
	v_exp_f32_e32 v7, v7
	v_lshlrev_b32_e32 v6, 16, v211
	v_add_f32_e32 v7, 1.0, v7
	v_div_scale_f32 v8, s[8:9], v7, v7, v6
	v_rcp_f32_e32 v9, v8
	v_div_scale_f32 v13, vcc, v6, v7, v6
	v_fma_f32 v14, -v8, v9, 1.0
	v_fmac_f32_e32 v9, v14, v9
	v_mul_f32_e32 v14, v13, v9
	v_fma_f32 v15, -v8, v14, v13
	v_fmac_f32_e32 v14, v15, v9
	v_fma_f32 v8, -v8, v14, v13
	v_div_fmas_f32 v8, v8, v9, v14
	v_div_fixup_f32 v26, v8, v7, v6
.LBB0_303:
	s_add_i32 s8, s1, -13
	v_mov_b32_e32 v24, 0
	s_cmpk_gt_u32 s8, 0xfff
	v_mov_b32_e32 v27, 0
	s_cbranch_scc1 .LBB0_305
	v_lshlrev_b32_e32 v7, 16, v212
	v_mul_f32_e32 v7, 0xbfb8aa3b, v7
	v_exp_f32_e32 v7, v7
	v_lshlrev_b32_e32 v6, 16, v213
	v_add_f32_e32 v7, 1.0, v7
	v_div_scale_f32 v8, s[8:9], v7, v7, v6
	v_rcp_f32_e32 v9, v8
	v_div_scale_f32 v13, vcc, v6, v7, v6
	v_fma_f32 v14, -v8, v9, 1.0
	v_fmac_f32_e32 v9, v14, v9
	v_mul_f32_e32 v14, v13, v9
	v_fma_f32 v15, -v8, v14, v13
	v_fmac_f32_e32 v14, v15, v9
	v_fma_f32 v8, -v8, v14, v13
	v_div_fmas_f32 v8, v8, v9, v14
	v_div_fixup_f32 v27, v8, v7, v6
.LBB0_305:
	s_add_i32 s8, s1, -12
	s_cmpk_gt_u32 s8, 0xfff
	s_cbranch_scc1 .LBB0_307
	v_lshlrev_b32_e32 v7, 16, v214
	v_mul_f32_e32 v7, 0xbfb8aa3b, v7
	v_exp_f32_e32 v7, v7
	v_lshlrev_b32_e32 v6, 16, v215
	v_add_f32_e32 v7, 1.0, v7
	v_div_scale_f32 v8, s[8:9], v7, v7, v6
	v_rcp_f32_e32 v9, v8
	v_div_scale_f32 v13, vcc, v6, v7, v6
	v_fma_f32 v14, -v8, v9, 1.0
	v_fmac_f32_e32 v9, v14, v9
	v_mul_f32_e32 v14, v13, v9
	v_fma_f32 v15, -v8, v14, v13
	v_fmac_f32_e32 v14, v15, v9
	v_fma_f32 v8, -v8, v14, v13
	v_div_fmas_f32 v8, v8, v9, v14
	v_div_fixup_f32 v24, v8, v7, v6
; __device__ __forceinline__ void conv_tile(const Params& p, int l, int item, const bf16* PROJ, bf16* CV, LAS float* sl) {
;     ...
;     for (int rr = 0; rr < 62; ++rr) { const int sq = s0 - 15 + rr; const bool ok = sq >= 0 && sq < SEQ; const bf16* pr = PROJ + (size_t)(b * SEQ + (ok ? sq : s0)) * NIN;
;         const float a = bf2f(pr[PB_A + c]), g = bf2f(pr[PB_G + c]); u[rr] = ok ? a / (1.0f + __expf(-g)) : 0.f; }
.LBB0_307:
	s_add_i32 s8, s1, -11
	v_mov_b32_e32 v22, 0
	s_cmpk_gt_u32 s8, 0xfff
	v_mov_b32_e32 v25, 0
	s_cbranch_scc1 .LBB0_309
	v_lshlrev_b32_e32 v7, 16, v216
	v_mul_f32_e32 v7, 0xbfb8aa3b, v7
	v_exp_f32_e32 v7, v7
	v_lshlrev_b32_e32 v6, 16, v217
	v_add_f32_e32 v7, 1.0, v7
	v_div_scale_f32 v8, s[8:9], v7, v7, v6
	v_rcp_f32_e32 v9, v8
	v_div_scale_f32 v13, vcc, v6, v7, v6
	v_fma_f32 v14, -v8, v9, 1.0
	v_fmac_f32_e32 v9, v14, v9
	v_mul_f32_e32 v14, v13, v9
	v_fma_f32 v15, -v8, v14, v13
	v_fmac_f32_e32 v14, v15, v9
	v_fma_f32 v8, -v8, v14, v13
	v_div_fmas_f32 v8, v8, v9, v14
	v_div_fixup_f32 v25, v8, v7, v6
.LBB0_309:
	s_add_i32 s8, s1, -10
	s_cmpk_gt_u32 s8, 0xfff
	s_cbranch_scc1 .LBB0_311
	v_lshlrev_b32_e32 v7, 16, v218
	v_mul_f32_e32 v7, 0xbfb8aa3b, v7
	v_exp_f32_e32 v7, v7
	v_lshlrev_b32_e32 v6, 16, v219
	v_add_f32_e32 v7, 1.0, v7
	v_div_scale_f32 v8, s[8:9], v7, v7, v6
	v_rcp_f32_e32 v9, v8
	v_div_scale_f32 v13, vcc, v6, v7, v6
	v_fma_f32 v14, -v8, v9, 1.0
	v_fmac_f32_e32 v9, v14, v9
	v_mul_f32_e32 v14, v13, v9
	v_fma_f32 v15, -v8, v14, v13
	v_fmac_f32_e32 v14, v15, v9
	v_fma_f32 v8, -v8, v14, v13
	v_div_fmas_f32 v8, v8, v9, v14
	v_div_fixup_f32 v22, v8, v7, v6
.LBB0_311:
	s_add_i32 s8, s1, -9
	v_mov_b32_e32 v20, 0
	s_cmpk_gt_u32 s8, 0xfff
	v_mov_b32_e32 v23, 0
	s_cbranch_scc1 .LBB0_313
	v_lshlrev_b32_e32 v7, 16, v220
	v_mul_f32_e32 v7, 0xbfb8aa3b, v7
	v_exp_f32_e32 v7, v7
	v_lshlrev_b32_e32 v6, 16, v221
	v_add_f32_e32 v7, 1.0, v7
	v_div_scale_f32 v8, s[8:9], v7, v7, v6
	v_rcp_f32_e32 v9, v8
	v_div_scale_f32 v13, vcc, v6, v7, v6
	v_fma_f32 v14, -v8, v9, 1.0
	v_fmac_f32_e32 v9, v14, v9
	v_mul_f32_e32 v14, v13, v9
	v_fma_f32 v15, -v8, v14, v13
	v_fmac_f32_e32 v14, v15, v9
	v_fma_f32 v8, -v8, v14, v13
	v_div_fmas_f32 v8, v8, v9, v14
	v_div_fixup_f32 v23, v8, v7, v6
.LBB0_313:
	s_add_i32 s8, s1, -8
	s_cmpk_gt_u32 s8, 0xfff
	s_cbranch_scc1 .LBB0_315
	v_lshlrev_b32_e32 v7, 16, v222
	v_mul_f32_e32 v7, 0xbfb8aa3b, v7
	v_exp_f32_e32 v7, v7
	v_lshlrev_b32_e32 v6, 16, v223
	v_add_f32_e32 v7, 1.0, v7
	v_div_scale_f32 v8, s[8:9], v7, v7, v6
	v_rcp_f32_e32 v9, v8
	v_div_scale_f32 v13, vcc, v6, v7, v6
	v_fma_f32 v14, -v8, v9, 1.0
	v_fmac_f32_e32 v9, v14, v9
	v_mul_f32_e32 v14, v13, v9
	v_fma_f32 v15, -v8, v14, v13
	v_fmac_f32_e32 v14, v15, v9
	v_fma_f32 v8, -v8, v14, v13
	v_div_fmas_f32 v8, v8, v9, v14
	v_div_fixup_f32 v20, v8, v7, v6
.LBB0_315:
	s_add_i32 s8, s1, -7
	v_mov_b32_e32 v18, 0
	s_cmpk_gt_u32 s8, 0xfff
	v_mov_b32_e32 v21, 0
	s_cbranch_scc1 .LBB0_317
	v_lshlrev_b32_e32 v7, 16, v224
	v_mul_f32_e32 v7, 0xbfb8aa3b, v7
	v_exp_f32_e32 v7, v7
	v_lshlrev_b32_e32 v6, 16, v225
	v_add_f32_e32 v7, 1.0, v7
	v_div_scale_f32 v8, s[8:9], v7, v7, v6
	v_rcp_f32_e32 v9, v8
	v_div_scale_f32 v13, vcc, v6, v7, v6
	v_fma_f32 v14, -v8, v9, 1.0
	v_fmac_f32_e32 v9, v14, v9
	v_mul_f32_e32 v14, v13, v9
	v_fma_f32 v15, -v8, v14, v13
	v_fmac_f32_e32 v14, v15, v9
	v_fma_f32 v8, -v8, v14, v13
	v_div_fmas_f32 v8, v8, v9, v14
	v_div_fixup_f32 v21, v8, v7, v6
.LBB0_317:
	s_add_i32 s8, s1, -6
	s_cmpk_gt_u32 s8, 0xfff
	s_cbranch_scc1 .LBB0_319
	v_lshlrev_b32_e32 v7, 16, v226
	v_mul_f32_e32 v7, 0xbfb8aa3b, v7
	v_exp_f32_e32 v7, v7
	v_lshlrev_b32_e32 v6, 16, v227
	v_add_f32_e32 v7, 1.0, v7
	v_div_scale_f32 v8, s[8:9], v7, v7, v6
	v_rcp_f32_e32 v9, v8
	v_div_scale_f32 v13, vcc, v6, v7, v6
	v_fma_f32 v14, -v8, v9, 1.0
	v_fmac_f32_e32 v9, v14, v9
	v_mul_f32_e32 v14, v13, v9
	v_fma_f32 v15, -v8, v14, v13
	v_fmac_f32_e32 v14, v15, v9
	v_fma_f32 v8, -v8, v14, v13
	v_div_fmas_f32 v8, v8, v9, v14
	v_div_fixup_f32 v18, v8, v7, v6
.LBB0_319:
	s_add_i32 s8, s1, -5
	v_mov_b32_e32 v16, 0
	s_cmpk_gt_u32 s8, 0xfff
	v_mov_b32_e32 v19, 0
	s_cbranch_scc1 .LBB0_321
	v_lshlrev_b32_e32 v7, 16, v228
	v_mul_f32_e32 v7, 0xbfb8aa3b, v7
	v_exp_f32_e32 v7, v7
	v_lshlrev_b32_e32 v6, 16, v229
	v_add_f32_e32 v7, 1.0, v7
	v_div_scale_f32 v8, s[8:9], v7, v7, v6
	v_rcp_f32_e32 v9, v8
	v_div_scale_f32 v13, vcc, v6, v7, v6
	v_fma_f32 v14, -v8, v9, 1.0
	v_fmac_f32_e32 v9, v14, v9
	v_mul_f32_e32 v14, v13, v9
	v_fma_f32 v15, -v8, v14, v13
	v_fmac_f32_e32 v14, v15, v9
	v_fma_f32 v8, -v8, v14, v13
	v_div_fmas_f32 v8, v8, v9, v14
	v_div_fixup_f32 v19, v8, v7, v6
.LBB0_321:
	s_add_i32 s8, s1, -4
	s_cmpk_gt_u32 s8, 0xfff
	s_cbranch_scc1 .LBB0_323
	v_lshlrev_b32_e32 v7, 16, v230
	v_mul_f32_e32 v7, 0xbfb8aa3b, v7
	v_exp_f32_e32 v7, v7
	v_lshlrev_b32_e32 v6, 16, v231
	v_add_f32_e32 v7, 1.0, v7
	v_div_scale_f32 v8, s[8:9], v7, v7, v6
	v_rcp_f32_e32 v9, v8
	v_div_scale_f32 v13, vcc, v6, v7, v6
	v_fma_f32 v14, -v8, v9, 1.0
	v_fmac_f32_e32 v9, v14, v9
	v_mul_f32_e32 v14, v13, v9
	v_fma_f32 v15, -v8, v14, v13
	v_fmac_f32_e32 v14, v15, v9
	v_fma_f32 v8, -v8, v14, v13
	v_div_fmas_f32 v8, v8, v9, v14
	v_div_fixup_f32 v16, v8, v7, v6
.LBB0_323:
	s_add_i32 s8, s1, -3
	v_mov_b32_e32 v14, 0
	s_cmpk_gt_u32 s8, 0xfff
	v_mov_b32_e32 v17, 0
	s_cbranch_scc1 .LBB0_325
	v_lshlrev_b32_e32 v7, 16, v232
	v_mul_f32_e32 v7, 0xbfb8aa3b, v7
	v_exp_f32_e32 v7, v7
	v_lshlrev_b32_e32 v6, 16, v233
	v_add_f32_e32 v7, 1.0, v7
	v_div_scale_f32 v8, s[8:9], v7, v7, v6
	v_rcp_f32_e32 v9, v8
	v_div_scale_f32 v13, vcc, v6, v7, v6
	v_fma_f32 v15, -v8, v9, 1.0
	v_fmac_f32_e32 v9, v15, v9
	v_mul_f32_e32 v15, v13, v9
	v_fma_f32 v17, -v8, v15, v13
	v_fmac_f32_e32 v15, v17, v9
	v_fma_f32 v8, -v8, v15, v13
	v_div_fmas_f32 v8, v8, v9, v15
	v_div_fixup_f32 v17, v8, v7, v6
.LBB0_325:
	s_add_i32 s8, s1, -2
	s_cmpk_gt_u32 s8, 0xfff
	s_cbranch_scc1 .LBB0_327
	v_lshlrev_b32_e32 v7, 16, v234
	v_mul_f32_e32 v7, 0xbfb8aa3b, v7
	v_exp_f32_e32 v7, v7
	v_lshlrev_b32_e32 v6, 16, v235
	v_add_f32_e32 v7, 1.0, v7
	v_div_scale_f32 v8, s[8:9], v7, v7, v6
	v_rcp_f32_e32 v9, v8
	v_div_scale_f32 v13, vcc, v6, v7, v6
	v_fma_f32 v14, -v8, v9, 1.0
	v_fmac_f32_e32 v9, v14, v9
	v_mul_f32_e32 v14, v13, v9
	v_fma_f32 v15, -v8, v14, v13
	v_fmac_f32_e32 v14, v15, v9
	v_fma_f32 v8, -v8, v14, v13
	v_div_fmas_f32 v8, v8, v9, v14
	v_div_fixup_f32 v14, v8, v7, v6
; __device__ __forceinline__ void conv_tile(const Params& p, int l, int item, const bf16* PROJ, bf16* CV, LAS float* sl) {
;     ...
;     for (int rr = 0; rr < 62; ++rr) { const int sq = s0 - 15 + rr; const bool ok = sq >= 0 && sq < SEQ; const bf16* pr = PROJ + (size_t)(b * SEQ + (ok ? sq : s0)) * NIN;
;         const float a = bf2f(pr[PB_A + c]), g = bf2f(pr[PB_G + c]); u[rr] = ok ? a / (1.0f + __expf(-g)) : 0.f; }
.LBB0_327:
	s_add_i32 s8, s1, -1
	v_mov_b32_e32 v6, 0
	s_cmpk_gt_u32 s8, 0xfff
	v_mov_b32_e32 v15, 0
	s_cbranch_scc1 .LBB0_329
	v_lshlrev_b32_e32 v7, 16, v236
	v_mul_f32_e32 v7, 0xbfb8aa3b, v7
	v_exp_f32_e32 v7, v7
	v_lshlrev_b32_e32 v8, 16, v237
	v_add_f32_e32 v7, 1.0, v7
	v_div_scale_f32 v9, s[8:9], v7, v7, v8
	v_rcp_f32_e32 v13, v9
	v_div_scale_f32 v15, vcc, v8, v7, v8
	v_fma_f32 v29, -v9, v13, 1.0
	v_fmac_f32_e32 v13, v29, v13
	v_mul_f32_e32 v29, v15, v13
	v_fma_f32 v30, -v9, v29, v15
	v_fmac_f32_e32 v29, v30, v13
	v_fma_f32 v9, -v9, v29, v15
	v_div_fmas_f32 v9, v9, v13, v29
	v_div_fixup_f32 v15, v9, v7, v8
.LBB0_329:
	v_readlane_b32 s80, v254, 62
	s_or_b32 s76, s80, 1
	s_or_b32 s74, s80, 2
	v_mad_u64_u32 v[8:9], s[8:9], s80, v195, v[4:5]
	v_add_co_u32_e32 v30, vcc, 0x1000, v8
	s_or_b32 s72, s80, 3
	s_nop 0
	v_addc_co_u32_e32 v31, vcc, 0, v9, vcc
	global_load_ushort v102, v[30:31], off
	global_load_ushort v101, v[8:9], off offset:3072
	v_mad_u64_u32 v[8:9], s[8:9], s76, v195, v[4:5]
	v_add_co_u32_e32 v30, vcc, 0x1000, v8
	s_or_b32 s70, s80, 4
	s_nop 0
	v_addc_co_u32_e32 v31, vcc, 0, v9, vcc
	global_load_ushort v100, v[30:31], off
	global_load_ushort v99, v[8:9], off offset:3072
	v_mad_u64_u32 v[8:9], s[8:9], s74, v195, v[4:5]
	v_add_co_u32_e32 v30, vcc, 0x1000, v8
	s_or_b32 s68, s80, 5
	s_nop 0
	v_addc_co_u32_e32 v31, vcc, 0, v9, vcc
	global_load_ushort v97, v[30:31], off
	s_nop 0
	global_load_ushort v30, v[8:9], off offset:3072
	v_mad_u64_u32 v[8:9], s[8:9], s72, v195, v[4:5]
	v_add_co_u32_e32 v32, vcc, 0x1000, v8
	s_or_b32 s66, s80, 6
	s_nop 0
	v_addc_co_u32_e32 v33, vcc, 0, v9, vcc
	global_load_ushort v98, v[32:33], off
	global_load_ushort v96, v[8:9], off offset:3072
	v_mad_u64_u32 v[8:9], s[8:9], s70, v195, v[4:5]
	v_add_co_u32_e32 v32, vcc, 0x1000, v8
	s_or_b32 s64, s80, 7
	s_nop 0
	v_addc_co_u32_e32 v33, vcc, 0, v9, vcc
	global_load_ushort v95, v[32:33], off
	global_load_ushort v94, v[8:9], off offset:3072
	v_mad_u64_u32 v[8:9], s[8:9], s68, v195, v[4:5]
	v_add_co_u32_e32 v32, vcc, 0x1000, v8
	s_or_b32 s62, s80, 8
	s_nop 0
	v_addc_co_u32_e32 v33, vcc, 0, v9, vcc
	global_load_ushort v93, v[32:33], off
	global_load_ushort v91, v[8:9], off offset:3072
	v_mad_u64_u32 v[8:9], s[8:9], s66, v195, v[4:5]
	v_add_co_u32_e32 v32, vcc, 0x1000, v8
	s_or_b32 s60, s80, 9
	s_nop 0
	v_addc_co_u32_e32 v33, vcc, 0, v9, vcc
	global_load_ushort v90, v[32:33], off
	global_load_ushort v81, v[8:9], off offset:3072
	v_mad_u64_u32 v[8:9], s[8:9], s64, v195, v[4:5]
	v_add_co_u32_e32 v32, vcc, 0x1000, v8
	s_or_b32 s58, s80, 10
	s_nop 0
	v_addc_co_u32_e32 v33, vcc, 0, v9, vcc
	global_load_ushort v92, v[32:33], off
	global_load_ushort v89, v[8:9], off offset:3072
	v_mad_u64_u32 v[8:9], s[8:9], s62, v195, v[4:5]
	v_add_co_u32_e32 v32, vcc, 0x1000, v8
	s_or_b32 s56, s80, 11
	s_nop 0
	v_addc_co_u32_e32 v33, vcc, 0, v9, vcc
	global_load_ushort v88, v[32:33], off
	global_load_ushort v77, v[8:9], off offset:3072
	v_mad_u64_u32 v[8:9], s[8:9], s60, v195, v[4:5]
	v_add_co_u32_e32 v32, vcc, 0x1000, v8
	s_or_b32 s54, s80, 12
	s_nop 0
	v_addc_co_u32_e32 v33, vcc, 0, v9, vcc
	global_load_ushort v87, v[32:33], off
	global_load_ushort v76, v[8:9], off offset:3072
	v_mad_u64_u32 v[8:9], s[8:9], s58, v195, v[4:5]
	v_add_co_u32_e32 v32, vcc, 0x1000, v8
	s_or_b32 s52, s80, 13
	s_nop 0
	v_addc_co_u32_e32 v33, vcc, 0, v9, vcc
	global_load_ushort v74, v[32:33], off
	global_load_ushort v71, v[8:9], off offset:3072
	v_mad_u64_u32 v[8:9], s[8:9], s56, v195, v[4:5]
	v_add_co_u32_e32 v32, vcc, 0x1000, v8
	s_or_b32 s50, s80, 14
	s_nop 0
	v_addc_co_u32_e32 v33, vcc, 0, v9, vcc
	global_load_ushort v86, v[32:33], off
	global_load_ushort v85, v[8:9], off offset:3072
	v_mad_u64_u32 v[8:9], s[8:9], s54, v195, v[4:5]
	v_add_co_u32_e32 v32, vcc, 0x1000, v8
	s_or_b32 s48, s80, 15
	s_nop 0
	v_addc_co_u32_e32 v33, vcc, 0, v9, vcc
	global_load_ushort v84, v[32:33], off
	global_load_ushort v69, v[8:9], off offset:3072
	v_mad_u64_u32 v[8:9], s[8:9], s52, v195, v[4:5]
	v_add_co_u32_e32 v32, vcc, 0x1000, v8
	s_or_b32 s46, s80, 16
	s_nop 0
	v_addc_co_u32_e32 v33, vcc, 0, v9, vcc
	global_load_ushort v83, v[32:33], off
	global_load_ushort v66, v[8:9], off offset:3072
	v_mad_u64_u32 v[8:9], s[8:9], s50, v195, v[4:5]
	v_add_co_u32_e32 v32, vcc, 0x1000, v8
	s_or_b32 s42, s80, 17
	s_nop 0
	v_addc_co_u32_e32 v33, vcc, 0, v9, vcc
	global_load_ushort v63, v[32:33], off
	global_load_ushort v61, v[8:9], off offset:3072
	v_mad_u64_u32 v[8:9], s[8:9], s48, v195, v[4:5]
	v_add_co_u32_e32 v32, vcc, 0x1000, v8
	s_or_b32 s40, s80, 18
	s_nop 0
	v_addc_co_u32_e32 v33, vcc, 0, v9, vcc
	global_load_ushort v82, v[32:33], off
	global_load_ushort v80, v[8:9], off offset:3072
	v_mad_u64_u32 v[8:9], s[8:9], s46, v195, v[4:5]
	v_add_co_u32_e32 v32, vcc, 0x1000, v8
	s_or_b32 s36, s80, 19
	s_nop 0
	v_addc_co_u32_e32 v33, vcc, 0, v9, vcc
; __device__ __forceinline__ void conv_tile(const Params& p, int l, int item, const bf16* PROJ, bf16* CV, LAS float* sl) {
;     ...
;     for (int rr = 0; rr < 62; ++rr) { const int sq = s0 - 15 + rr; const bool ok = sq >= 0 && sq < SEQ; const bf16* pr = PROJ + (size_t)(b * SEQ + (ok ? sq : s0)) * NIN;
;         const float a = bf2f(pr[PB_A + c]), g = bf2f(pr[PB_G + c]); u[rr] = ok ? a / (1.0f + __expf(-g)) : 0.f; }
	global_load_ushort v79, v[32:33], off
	global_load_ushort v58, v[8:9], off offset:3072
	v_mad_u64_u32 v[8:9], s[8:9], s42, v195, v[4:5]
	v_add_co_u32_e32 v32, vcc, 0x1000, v8
	s_or_b32 s34, s80, 20
	s_nop 0
	v_addc_co_u32_e32 v33, vcc, 0, v9, vcc
	global_load_ushort v78, v[32:33], off
	global_load_ushort v56, v[8:9], off offset:3072
	v_mad_u64_u32 v[8:9], s[8:9], s40, v195, v[4:5]
	v_add_co_u32_e32 v32, vcc, 0x1000, v8
	s_or_b32 s30, s80, 21
	s_nop 0
	v_addc_co_u32_e32 v33, vcc, 0, v9, vcc
	global_load_ushort v73, v[32:33], off
	global_load_ushort v57, v[8:9], off offset:3072
	v_mad_u64_u32 v[8:9], s[8:9], s36, v195, v[4:5]
	v_add_co_u32_e32 v32, vcc, 0x1000, v8
	s_or_b32 s28, s80, 22
	s_nop 0
	v_addc_co_u32_e32 v33, vcc, 0, v9, vcc
	global_load_ushort v75, v[32:33], off
	global_load_ushort v59, v[8:9], off offset:3072
	v_mad_u64_u32 v[8:9], s[8:9], s34, v195, v[4:5]
	v_add_co_u32_e32 v32, vcc, 0x1000, v8
	s_or_b32 s26, s80, 23
	s_nop 0
	v_addc_co_u32_e32 v33, vcc, 0, v9, vcc
	global_load_ushort v72, v[32:33], off
	global_load_ushort v60, v[8:9], off offset:3072
	v_mad_u64_u32 v[8:9], s[8:9], s30, v195, v[4:5]
	v_add_co_u32_e32 v32, vcc, 0x1000, v8
	s_or_b32 s24, s80, 24
	s_nop 0
	v_addc_co_u32_e32 v33, vcc, 0, v9, vcc
	global_load_ushort v70, v[32:33], off
	global_load_ushort v62, v[8:9], off offset:3072
	v_mad_u64_u32 v[8:9], s[8:9], s28, v195, v[4:5]
	v_add_co_u32_e32 v32, vcc, 0x1000, v8
	s_or_b32 s22, s80, 25
	s_nop 0
	v_addc_co_u32_e32 v33, vcc, 0, v9, vcc
	global_load_ushort v67, v[32:33], off
	global_load_ushort v64, v[8:9], off offset:3072
	v_mad_u64_u32 v[8:9], s[8:9], s26, v195, v[4:5]
	v_add_co_u32_e32 v32, vcc, 0x1000, v8
	s_or_b32 s20, s80, 26
	s_nop 0
	v_addc_co_u32_e32 v33, vcc, 0, v9, vcc
	global_load_ushort v68, v[32:33], off
	global_load_ushort v65, v[8:9], off offset:3072
	v_mad_u64_u32 v[8:9], s[8:9], s24, v195, v[4:5]
	v_add_co_u32_e32 v32, vcc, 0x1000, v8
	s_or_b32 s18, s80, 27
	s_nop 0
	v_addc_co_u32_e32 v33, vcc, 0, v9, vcc
	global_load_ushort v55, v[32:33], off
	global_load_ushort v54, v[8:9], off offset:3072
	v_mad_u64_u32 v[8:9], s[8:9], s22, v195, v[4:5]
	v_add_co_u32_e32 v32, vcc, 0x1000, v8
	s_or_b32 s16, s80, 28
	s_nop 0
	v_addc_co_u32_e32 v33, vcc, 0, v9, vcc
	global_load_ushort v53, v[32:33], off
	global_load_ushort v52, v[8:9], off offset:3072
	v_mad_u64_u32 v[8:9], s[8:9], s20, v195, v[4:5]
	v_add_co_u32_e32 v32, vcc, 0x1000, v8
	s_or_b32 s14, s80, 29
	s_nop 0
	v_addc_co_u32_e32 v33, vcc, 0, v9, vcc
	global_load_ushort v44, v[32:33], off
	global_load_ushort v38, v[8:9], off offset:3072
	v_mad_u64_u32 v[8:9], s[8:9], s18, v195, v[4:5]
	v_add_co_u32_e32 v32, vcc, 0x1000, v8
	s_or_b32 s12, s80, 30
	s_nop 0
	v_addc_co_u32_e32 v33, vcc, 0, v9, vcc
	global_load_ushort v47, v[32:33], off
	global_load_ushort v41, v[8:9], off offset:3072
	v_mad_u64_u32 v[8:9], s[8:9], s16, v195, v[4:5]
	v_add_co_u32_e32 v32, vcc, 0x1000, v8
	v_readlane_b32 s81, v254, 63
	s_nop 0
	v_addc_co_u32_e32 v33, vcc, 0, v9, vcc
	global_load_ushort v37, v[32:33], off
	global_load_ushort v36, v[8:9], off offset:3072
	v_mad_u64_u32 v[8:9], s[8:9], s14, v195, v[4:5]
	v_add_co_u32_e32 v32, vcc, 0x1000, v8
	v_readlane_b32 s82, v255, 0
	s_nop 0
	v_addc_co_u32_e32 v33, vcc, 0, v9, vcc
	global_load_ushort v34, v[32:33], off
	global_load_ushort v13, v[8:9], off offset:3072
	v_mad_u64_u32 v[8:9], s[8:9], s12, v195, v[4:5]
	v_add_co_u32_e32 v32, vcc, 0x1000, v8
	s_or_b32 s8, s80, 31
	s_nop 0
	v_addc_co_u32_e32 v33, vcc, 0, v9, vcc
	global_load_ushort v31, v[32:33], off
	global_load_ushort v29, v[8:9], off offset:3072
	v_mad_u64_u32 v[8:9], s[78:79], s8, v195, v[4:5]
	v_add_co_u32_e32 v32, vcc, 0x1000, v8
	s_cmpk_eq_i32 s1, 0xfe0
	s_nop 0
	v_addc_co_u32_e32 v33, vcc, 0, v9, vcc
	global_load_ushort v33, v[32:33], off
	s_nop 0
	global_load_ushort v32, v[8:9], off offset:3072
	v_readlane_b32 s83, v255, 1
	v_readlane_b32 s84, v255, 2
	v_readlane_b32 s85, v255, 3
	v_readlane_b32 s86, v255, 4
	v_readlane_b32 s87, v255, 5
	v_readlane_b32 s88, v255, 6
	v_readlane_b32 s89, v255, 7
	v_readlane_b32 s90, v255, 8
	v_readlane_b32 s91, v255, 9
	v_readlane_b32 s92, v255, 10
	v_readlane_b32 s93, v255, 11
	v_readlane_b32 s94, v255, 12
	v_readlane_b32 s95, v255, 13
	s_cbranch_scc1 .LBB0_352
	v_lshlrev_b32_e32 v7, 16, v238
	v_mul_f32_e32 v7, 0xbfb8aa3b, v7
	v_exp_f32_e32 v7, v7
	v_lshlrev_b32_e32 v6, 16, v239
	v_add_f32_e32 v7, 1.0, v7
	v_div_scale_f32 v8, s[78:79], v7, v7, v6
	v_rcp_f32_e32 v9, v8
	v_div_scale_f32 v35, vcc, v6, v7, v6
	v_fma_f32 v39, -v8, v9, 1.0
	v_fmac_f32_e32 v9, v39, v9
	v_mul_f32_e32 v39, v35, v9
	v_fma_f32 v40, -v8, v39, v35
	v_fmac_f32_e32 v39, v40, v9
	v_fma_f32 v8, -v8, v39, v35
	v_div_fmas_f32 v8, v8, v9, v39
	v_div_fixup_f32 v6, v8, v7, v6
	v_mov_b32_e32 v7, 0
	s_cmpk_gt_u32 s1, 0xfde
	v_mov_b32_e32 v8, 0
	s_cbranch_scc0 .LBB0_353

; __device__ __forceinline__ void conv_tile(const Params& p, int l, int item, const bf16* PROJ, bf16* CV, LAS float* sl) {
;     ...
;     for (int rr = 0; rr < 62; ++rr) { const int sq = s0 - 15 + rr; const bool ok = sq >= 0 && sq < SEQ; const bf16* pr = PROJ + (size_t)(b * SEQ + (ok ? sq : s0)) * NIN;
;         const float a = bf2f(pr[PB_A + c]), g = bf2f(pr[PB_G + c]); u[rr] = ok ? a / (1.0f + __expf(-g)) : 0.f; }
.LBB0_332:
	v_lshlrev_b32_e32 v7, 16, v242
	v_mul_f32_e32 v7, 0xbfb8aa3b, v7
	v_exp_f32_e32 v7, v7
	v_lshlrev_b32_e32 v9, 16, v243
	v_add_f32_e32 v7, 1.0, v7
	v_div_scale_f32 v35, s[78:79], v7, v7, v9
	v_rcp_f32_e32 v39, v35
	v_div_scale_f32 v40, vcc, v9, v7, v9
	v_fma_f32 v42, -v35, v39, 1.0
	v_fmac_f32_e32 v39, v42, v39
	v_mul_f32_e32 v42, v40, v39
	v_fma_f32 v43, -v35, v42, v40
	v_fmac_f32_e32 v42, v43, v39
	v_fma_f32 v35, -v35, v42, v40
	v_div_fmas_f32 v35, v35, v39, v42
	v_div_fixup_f32 v7, v35, v7, v9
	v_mov_b32_e32 v9, 0
	s_cmpk_gt_u32 s1, 0xfdc
	v_mov_b32_e32 v35, 0
	s_cbranch_scc0 .LBB0_355

; __device__ __forceinline__ void conv_tile(const Params& p, int l, int item, const bf16* PROJ, bf16* CV, LAS float* sl) {
;     ...
;     for (int rr = 0; rr < 62; ++rr) { const int sq = s0 - 15 + rr; const bool ok = sq >= 0 && sq < SEQ; const bf16* pr = PROJ + (size_t)(b * SEQ + (ok ? sq : s0)) * NIN;
;         const float a = bf2f(pr[PB_A + c]), g = bf2f(pr[PB_G + c]); u[rr] = ok ? a / (1.0f + __expf(-g)) : 0.f; }
.LBB0_334:
	v_lshlrev_b32_e32 v9, 16, v246
	v_mul_f32_e32 v9, 0xbfb8aa3b, v9
	v_exp_f32_e32 v9, v9
	v_lshlrev_b32_e32 v39, 16, v247
	v_add_f32_e32 v9, 1.0, v9
	v_div_scale_f32 v40, s[78:79], v9, v9, v39
	v_rcp_f32_e32 v42, v40
	v_div_scale_f32 v43, vcc, v39, v9, v39
	v_fma_f32 v45, -v40, v42, 1.0
	v_fmac_f32_e32 v42, v45, v42
	v_mul_f32_e32 v45, v43, v42
	v_fma_f32 v46, -v40, v45, v43
	v_fmac_f32_e32 v45, v46, v42
	v_fma_f32 v40, -v40, v45, v43
	v_div_fmas_f32 v40, v40, v42, v45
	v_div_fixup_f32 v9, v40, v9, v39
	v_mov_b32_e32 v39, 0
	s_cmpk_gt_u32 s1, 0xfda
	v_mov_b32_e32 v40, 0
	s_cbranch_scc0 .LBB0_357

; __device__ __forceinline__ void conv_tile(const Params& p, int l, int item, const bf16* PROJ, bf16* CV, LAS float* sl) {
;     ...
;     for (int rr = 0; rr < 62; ++rr) { const int sq = s0 - 15 + rr; const bool ok = sq >= 0 && sq < SEQ; const bf16* pr = PROJ + (size_t)(b * SEQ + (ok ? sq : s0)) * NIN;
;         const float a = bf2f(pr[PB_A + c]), g = bf2f(pr[PB_G + c]); u[rr] = ok ? a / (1.0f + __expf(-g)) : 0.f; }
.LBB0_336:
	v_lshlrev_b32_e32 v39, 16, v141
	v_mul_f32_e32 v39, 0xbfb8aa3b, v39
	v_exp_f32_e32 v39, v39
	v_lshlrev_b32_e32 v42, 16, v142
	v_add_f32_e32 v39, 1.0, v39
	v_div_scale_f32 v43, s[78:79], v39, v39, v42
	v_rcp_f32_e32 v45, v43
	v_div_scale_f32 v46, vcc, v42, v39, v42
	v_fma_f32 v48, -v43, v45, 1.0
	v_fmac_f32_e32 v45, v48, v45
	v_mul_f32_e32 v48, v46, v45
	v_fma_f32 v49, -v43, v48, v46
	v_fmac_f32_e32 v48, v49, v45
	v_fma_f32 v43, -v43, v48, v46
	v_div_fmas_f32 v43, v43, v45, v48
	v_div_fixup_f32 v39, v43, v39, v42
	v_mov_b32_e32 v42, 0
	s_cmpk_gt_u32 s1, 0xfd8
	v_mov_b32_e32 v43, 0
	s_cbranch_scc0 .LBB0_359

; __device__ __forceinline__ void conv_tile(const Params& p, int l, int item, const bf16* PROJ, bf16* CV, LAS float* sl) {
;     ...
;     for (int rr = 0; rr < 62; ++rr) { const int sq = s0 - 15 + rr; const bool ok = sq >= 0 && sq < SEQ; const bf16* pr = PROJ + (size_t)(b * SEQ + (ok ? sq : s0)) * NIN;
;         const float a = bf2f(pr[PB_A + c]), g = bf2f(pr[PB_G + c]); u[rr] = ok ? a / (1.0f + __expf(-g)) : 0.f; }
.LBB0_338:
	v_lshlrev_b32_e32 v42, 16, v145
	v_mul_f32_e32 v42, 0xbfb8aa3b, v42
	v_exp_f32_e32 v42, v42
	v_lshlrev_b32_e32 v45, 16, v146
	v_add_f32_e32 v42, 1.0, v42
	v_div_scale_f32 v46, s[78:79], v42, v42, v45
	v_rcp_f32_e32 v48, v46
	v_div_scale_f32 v49, vcc, v45, v42, v45
	v_fma_f32 v50, -v46, v48, 1.0
	v_fmac_f32_e32 v48, v50, v48
	v_mul_f32_e32 v50, v49, v48
	v_fma_f32 v51, -v46, v50, v49
	v_fmac_f32_e32 v50, v51, v48
	v_fma_f32 v46, -v46, v50, v49
	v_div_fmas_f32 v46, v46, v48, v50
	v_div_fixup_f32 v42, v46, v42, v45
	v_mov_b32_e32 v45, 0
	s_cmpk_gt_u32 s1, 0xfd6
	v_mov_b32_e32 v46, 0
	s_cbranch_scc0 .LBB0_361

; __device__ __forceinline__ void conv_tile(const Params& p, int l, int item, const bf16* PROJ, bf16* CV, LAS float* sl) {
;     ...
;     for (int rr = 0; rr < 62; ++rr) { const int sq = s0 - 15 + rr; const bool ok = sq >= 0 && sq < SEQ; const bf16* pr = PROJ + (size_t)(b * SEQ + (ok ? sq : s0)) * NIN;
;         const float a = bf2f(pr[PB_A + c]), g = bf2f(pr[PB_G + c]); u[rr] = ok ? a / (1.0f + __expf(-g)) : 0.f; }
.LBB0_340:
	v_lshlrev_b32_e32 v45, 16, v149
	v_mul_f32_e32 v45, 0xbfb8aa3b, v45
	v_exp_f32_e32 v45, v45
	v_lshlrev_b32_e32 v48, 16, v150
	v_add_f32_e32 v45, 1.0, v45
	v_div_scale_f32 v49, s[78:79], v45, v45, v48
	v_rcp_f32_e32 v50, v49
	v_div_scale_f32 v51, vcc, v48, v45, v48
	v_fma_f32 v103, -v49, v50, 1.0
	v_fmac_f32_e32 v50, v103, v50
	v_mul_f32_e32 v103, v51, v50
	v_fma_f32 v104, -v49, v103, v51
	v_fmac_f32_e32 v103, v104, v50
	v_fma_f32 v49, -v49, v103, v51
	v_div_fmas_f32 v49, v49, v50, v103
	v_div_fixup_f32 v45, v49, v45, v48
	v_mov_b32_e32 v48, 0
	s_cmpk_gt_u32 s1, 0xfd4
	v_mov_b32_e32 v49, 0
	s_cbranch_scc0 .LBB0_363

; __device__ __forceinline__ void conv_tile(const Params& p, int l, int item, const bf16* PROJ, bf16* CV, LAS float* sl) {
;     ...
;     for (int rr = 0; rr < 62; ++rr) { const int sq = s0 - 15 + rr; const bool ok = sq >= 0 && sq < SEQ; const bf16* pr = PROJ + (size_t)(b * SEQ + (ok ? sq : s0)) * NIN;
;         const float a = bf2f(pr[PB_A + c]), g = bf2f(pr[PB_G + c]); u[rr] = ok ? a / (1.0f + __expf(-g)) : 0.f; }
.LBB0_342:
	v_lshlrev_b32_e32 v48, 16, v153
	v_mul_f32_e32 v48, 0xbfb8aa3b, v48
	v_exp_f32_e32 v48, v48
	v_lshlrev_b32_e32 v50, 16, v156
	v_add_f32_e32 v48, 1.0, v48
	v_div_scale_f32 v51, s[78:79], v48, v48, v50
	v_rcp_f32_e32 v103, v51
	v_div_scale_f32 v104, vcc, v50, v48, v50
	v_fma_f32 v105, -v51, v103, 1.0
	v_fmac_f32_e32 v103, v105, v103
	v_mul_f32_e32 v105, v104, v103
	v_fma_f32 v106, -v51, v105, v104
	v_fmac_f32_e32 v105, v106, v103
	v_fma_f32 v51, -v51, v105, v104
	v_div_fmas_f32 v51, v51, v103, v105
	v_div_fixup_f32 v48, v51, v48, v50
	v_mov_b32_e32 v50, 0
	s_cmpk_gt_u32 s1, 0xfd2
	v_mov_b32_e32 v51, 0
	s_cbranch_scc0 .LBB0_365

; __device__ __forceinline__ void conv_tile(const Params& p, int l, int item, const bf16* PROJ, bf16* CV, LAS float* sl) {
;     ...
;     for (int rr = 0; rr < 62; ++rr) { const int sq = s0 - 15 + rr; const bool ok = sq >= 0 && sq < SEQ; const bf16* pr = PROJ + (size_t)(b * SEQ + (ok ? sq : s0)) * NIN;
;         const float a = bf2f(pr[PB_A + c]), g = bf2f(pr[PB_G + c]); u[rr] = ok ? a / (1.0f + __expf(-g)) : 0.f; }
.LBB0_344:
	v_lshlrev_b32_e32 v5, 16, v159
	v_mul_f32_e32 v5, 0xbfb8aa3b, v5
	v_exp_f32_e32 v5, v5
	v_lshlrev_b32_e32 v4, 16, v160
	v_add_f32_e32 v5, 1.0, v5
	v_div_scale_f32 v50, s[0:1], v5, v5, v4
	v_rcp_f32_e32 v103, v50
	v_div_scale_f32 v104, vcc, v4, v5, v4
	v_fma_f32 v105, -v50, v103, 1.0
	v_fmac_f32_e32 v103, v105, v103
	v_mul_f32_e32 v105, v104, v103
	v_fma_f32 v106, -v50, v105, v104
	v_fmac_f32_e32 v105, v106, v103
	v_fma_f32 v50, -v50, v105, v104
	v_div_fmas_f32 v50, v50, v103, v105
	v_div_fixup_f32 v50, v50, v5, v4

; __device__ __forceinline__ void conv_tile(const Params& p, int l, int item, const bf16* PROJ, bf16* CV, LAS float* sl) {
;     ...
;     for (int rr = 0; rr < 62; ++rr) { const int sq = s0 - 15 + rr; const bool ok = sq >= 0 && sq < SEQ; const bf16* pr = PROJ + (size_t)(b * SEQ + (ok ? sq : s0)) * NIN;
;         const float a = bf2f(pr[PB_A + c]), g = bf2f(pr[PB_G + c]); u[rr] = ok ? a / (1.0f + __expf(-g)) : 0.f; }
.LBB0_353:
	v_lshlrev_b32_e32 v9, 16, v240
	v_mul_f32_e32 v9, 0xbfb8aa3b, v9
	v_exp_f32_e32 v9, v9
	v_lshlrev_b32_e32 v8, 16, v241
	v_add_f32_e32 v9, 1.0, v9
	v_div_scale_f32 v35, s[78:79], v9, v9, v8
	v_rcp_f32_e32 v39, v35
	v_div_scale_f32 v40, vcc, v8, v9, v8
	v_fma_f32 v42, -v35, v39, 1.0
	v_fmac_f32_e32 v39, v42, v39
	v_mul_f32_e32 v42, v40, v39
	v_fma_f32 v43, -v35, v42, v40
	v_fmac_f32_e32 v42, v43, v39
	v_fma_f32 v35, -v35, v42, v40
	v_div_fmas_f32 v35, v35, v39, v42
	v_div_fixup_f32 v8, v35, v9, v8
	s_cmpk_gt_u32 s1, 0xfdd
	s_cbranch_scc0 .LBB0_332

; __device__ __forceinline__ void conv_tile(const Params& p, int l, int item, const bf16* PROJ, bf16* CV, LAS float* sl) {
;     ...
;     for (int rr = 0; rr < 62; ++rr) { const int sq = s0 - 15 + rr; const bool ok = sq >= 0 && sq < SEQ; const bf16* pr = PROJ + (size_t)(b * SEQ + (ok ? sq : s0)) * NIN;
;         const float a = bf2f(pr[PB_A + c]), g = bf2f(pr[PB_G + c]); u[rr] = ok ? a / (1.0f + __expf(-g)) : 0.f; }
.LBB0_355:
	v_lshlrev_b32_e32 v35, 16, v244
	v_mul_f32_e32 v35, 0xbfb8aa3b, v35
	v_exp_f32_e32 v35, v35
	v_lshlrev_b32_e32 v39, 16, v245
	v_add_f32_e32 v35, 1.0, v35
	v_div_scale_f32 v40, s[78:79], v35, v35, v39
	v_rcp_f32_e32 v42, v40
	v_div_scale_f32 v43, vcc, v39, v35, v39
	v_fma_f32 v45, -v40, v42, 1.0
	v_fmac_f32_e32 v42, v45, v42
	v_mul_f32_e32 v45, v43, v42
	v_fma_f32 v46, -v40, v45, v43
	v_fmac_f32_e32 v45, v46, v42
	v_fma_f32 v40, -v40, v45, v43
	v_div_fmas_f32 v40, v40, v42, v45
	v_div_fixup_f32 v35, v40, v35, v39
	s_cmpk_gt_u32 s1, 0xfdb
	s_cbranch_scc0 .LBB0_334

; __device__ __forceinline__ void conv_tile(const Params& p, int l, int item, const bf16* PROJ, bf16* CV, LAS float* sl) {
;     ...
;     for (int rr = 0; rr < 62; ++rr) { const int sq = s0 - 15 + rr; const bool ok = sq >= 0 && sq < SEQ; const bf16* pr = PROJ + (size_t)(b * SEQ + (ok ? sq : s0)) * NIN;
;         const float a = bf2f(pr[PB_A + c]), g = bf2f(pr[PB_G + c]); u[rr] = ok ? a / (1.0f + __expf(-g)) : 0.f; }
.LBB0_357:
	v_lshlrev_b32_e32 v40, 16, v248
	v_mul_f32_e32 v40, 0xbfb8aa3b, v40
	v_exp_f32_e32 v40, v40
	v_lshlrev_b32_e32 v42, 16, v249
	v_add_f32_e32 v40, 1.0, v40
	v_div_scale_f32 v43, s[78:79], v40, v40, v42
	v_rcp_f32_e32 v45, v43
	v_div_scale_f32 v46, vcc, v42, v40, v42
	v_fma_f32 v48, -v43, v45, 1.0
	v_fmac_f32_e32 v45, v48, v45
	v_mul_f32_e32 v48, v46, v45
	v_fma_f32 v49, -v43, v48, v46
	v_fmac_f32_e32 v48, v49, v45
	v_fma_f32 v43, -v43, v48, v46
	v_div_fmas_f32 v43, v43, v45, v48
	v_div_fixup_f32 v40, v43, v40, v42
	s_cmpk_gt_u32 s1, 0xfd9
	s_cbranch_scc0 .LBB0_336

; __device__ __forceinline__ void conv_tile(const Params& p, int l, int item, const bf16* PROJ, bf16* CV, LAS float* sl) {
;     ...
;     for (int rr = 0; rr < 62; ++rr) { const int sq = s0 - 15 + rr; const bool ok = sq >= 0 && sq < SEQ; const bf16* pr = PROJ + (size_t)(b * SEQ + (ok ? sq : s0)) * NIN;
;         const float a = bf2f(pr[PB_A + c]), g = bf2f(pr[PB_G + c]); u[rr] = ok ? a / (1.0f + __expf(-g)) : 0.f; }
.LBB0_359:
	v_lshlrev_b32_e32 v43, 16, v143
	v_mul_f32_e32 v43, 0xbfb8aa3b, v43
	v_exp_f32_e32 v43, v43
	v_lshlrev_b32_e32 v45, 16, v144
	v_add_f32_e32 v43, 1.0, v43
	v_div_scale_f32 v46, s[78:79], v43, v43, v45
	v_rcp_f32_e32 v48, v46
	v_div_scale_f32 v49, vcc, v45, v43, v45
	v_fma_f32 v50, -v46, v48, 1.0
	v_fmac_f32_e32 v48, v50, v48
	v_mul_f32_e32 v50, v49, v48
	v_fma_f32 v51, -v46, v50, v49
	v_fmac_f32_e32 v50, v51, v48
	v_fma_f32 v46, -v46, v50, v49
	v_div_fmas_f32 v46, v46, v48, v50
	v_div_fixup_f32 v43, v46, v43, v45
	s_cmpk_gt_u32 s1, 0xfd7
	s_cbranch_scc0 .LBB0_338

; __device__ __forceinline__ void conv_tile(const Params& p, int l, int item, const bf16* PROJ, bf16* CV, LAS float* sl) {
;     ...
;     for (int rr = 0; rr < 62; ++rr) { const int sq = s0 - 15 + rr; const bool ok = sq >= 0 && sq < SEQ; const bf16* pr = PROJ + (size_t)(b * SEQ + (ok ? sq : s0)) * NIN;
;         const float a = bf2f(pr[PB_A + c]), g = bf2f(pr[PB_G + c]); u[rr] = ok ? a / (1.0f + __expf(-g)) : 0.f; }
.LBB0_361:
	v_lshlrev_b32_e32 v46, 16, v147
	v_mul_f32_e32 v46, 0xbfb8aa3b, v46
	v_exp_f32_e32 v46, v46
	v_lshlrev_b32_e32 v48, 16, v148
	v_add_f32_e32 v46, 1.0, v46
	v_div_scale_f32 v49, s[78:79], v46, v46, v48
	v_rcp_f32_e32 v50, v49
	v_div_scale_f32 v51, vcc, v48, v46, v48
	v_fma_f32 v103, -v49, v50, 1.0
	v_fmac_f32_e32 v50, v103, v50
	v_mul_f32_e32 v103, v51, v50
	v_fma_f32 v104, -v49, v103, v51
	v_fmac_f32_e32 v103, v104, v50
	v_fma_f32 v49, -v49, v103, v51
	v_div_fmas_f32 v49, v49, v50, v103
	v_div_fixup_f32 v46, v49, v46, v48
	s_cmpk_gt_u32 s1, 0xfd5
	s_cbranch_scc0 .LBB0_340

; __device__ __forceinline__ void conv_tile(const Params& p, int l, int item, const bf16* PROJ, bf16* CV, LAS float* sl) {
;     ...
;     for (int rr = 0; rr < 62; ++rr) { const int sq = s0 - 15 + rr; const bool ok = sq >= 0 && sq < SEQ; const bf16* pr = PROJ + (size_t)(b * SEQ + (ok ? sq : s0)) * NIN;
;         const float a = bf2f(pr[PB_A + c]), g = bf2f(pr[PB_G + c]); u[rr] = ok ? a / (1.0f + __expf(-g)) : 0.f; }
.LBB0_363:
	v_lshlrev_b32_e32 v49, 16, v151
	v_mul_f32_e32 v49, 0xbfb8aa3b, v49
	v_exp_f32_e32 v49, v49
	v_lshlrev_b32_e32 v50, 16, v152
	v_add_f32_e32 v49, 1.0, v49
	v_div_scale_f32 v51, s[78:79], v49, v49, v50
	v_rcp_f32_e32 v103, v51
	v_div_scale_f32 v104, vcc, v50, v49, v50
	v_fma_f32 v105, -v51, v103, 1.0
	v_fmac_f32_e32 v103, v105, v103
	v_mul_f32_e32 v105, v104, v103
	v_fma_f32 v106, -v51, v105, v104
	v_fmac_f32_e32 v105, v106, v103
	v_fma_f32 v51, -v51, v105, v104
	v_div_fmas_f32 v51, v51, v103, v105
	v_div_fixup_f32 v49, v51, v49, v50
	s_cmpk_gt_u32 s1, 0xfd3
	s_cbranch_scc0 .LBB0_342

; __device__ __forceinline__ void conv_tile(const Params& p, int l, int item, const bf16* PROJ, bf16* CV, LAS float* sl) {
;     ...
;     for (int rr = 0; rr < 62; ++rr) { const int sq = s0 - 15 + rr; const bool ok = sq >= 0 && sq < SEQ; const bf16* pr = PROJ + (size_t)(b * SEQ + (ok ? sq : s0)) * NIN;
;         const float a = bf2f(pr[PB_A + c]), g = bf2f(pr[PB_G + c]); u[rr] = ok ? a / (1.0f + __expf(-g)) : 0.f; }
.LBB0_365:
	v_lshlrev_b32_e32 v51, 16, v157
	v_mul_f32_e32 v51, 0xbfb8aa3b, v51
	v_exp_f32_e32 v51, v51
	v_lshlrev_b32_e32 v103, 16, v158
	v_add_f32_e32 v51, 1.0, v51
	v_div_scale_f32 v104, s[78:79], v51, v51, v103
	v_rcp_f32_e32 v105, v104
	v_div_scale_f32 v106, vcc, v103, v51, v103
	v_fma_f32 v107, -v104, v105, 1.0
	v_fmac_f32_e32 v105, v107, v105
	v_mul_f32_e32 v107, v106, v105
	v_fma_f32 v108, -v104, v107, v106
	v_fmac_f32_e32 v107, v108, v105
	v_fma_f32 v104, -v104, v107, v106
	v_div_fmas_f32 v104, v104, v105, v107
	v_div_fixup_f32 v51, v104, v51, v103
	s_cmpk_gt_u32 s1, 0xfd1
	s_cbranch_scc0 .LBB0_344
	s_branch .LBB0_345

; __device__ __forceinline__ int crow(int r, int hi) { return (r & 3) + 8 * (r >> 2) + 4 * hi; }
; template <int DK, bool QL>
; __device__ __forceinline__ void qkt(f32x16& p0, f32x16& p1, const bf16* Ks, const bf16x8* qr, const char* ql, int r32, int hi) {
;   p0 = f32x16{}; p1 = f32x16{};
; #pragma unroll
;   for (int d0 = 0; d0 < DK / 16; ++d0) { int cb = (d0 * 16 + hi * 8) * 2;
;     const bf16x8 qv = QL ? *reinterpret_cast<const bf16x8*>(ql + d0 * 1024) : qr[d0];
;     bf16x8 b0 = *reinterpret_cast<const bf16x8*>((const char*)Ks + kswz<DK>(r32, cb));
;     bf16x8 b1 = *reinterpret_cast<const bf16x8*>((const char*)Ks + kswz<DK>(32 + r32, cb));
;     p0 = __builtin_amdgcn_mfma_f32_32x32x16_bf16(b0, qv, p0, 0, 0, 0);
;     p1 = __builtin_amdgcn_mfma_f32_32x32x16_bf16(b1, qv, p1, 0, 0, 0); }
; __device__ __forceinline__ void na_hook(f32x16& p0, f32x16& p1, int kr, int q_row, int q_col, int win_r, int win_c, const float* rpb, float inv_scale, int hi) {
;   const bool rowok = (kr >= win_r) && (kr < win_r + 8);
;   int ir = kr - q_row + 7; ir = ir < 0 ? 0 : (ir > 14 ? 14 : ir);
;   const float* rp = rpb + ir * 31;
; #pragma unroll
;   for (int r = 0; r < 16; ++r) {
;     const int kc = crow(r, hi);
;     { const bool ok = rowok && kc >= win_c && kc < win_c + 16; int ic = kc - q_col + 15; ic = ic < 0 ? 0 : (ic > 30 ? 30 : ic);
;       p0[r] = ok ? fmaf(rp[ic], inv_scale, p0[r]) : -1e30f; }
;     { const int kc2 = kc + 32; const bool ok = rowok && kc2 >= win_c && kc2 < win_c + 16; int ic = kc2 - q_col + 15; ic = ic < 0 ? 0 : (ic > 30 ? 30 : ic);
;       p1[r] = ok ? fmaf(rp[ic], inv_scale, p1[r]) : -1e30f; }
;   }
; }
.LBB0_449:
	ds_read_b128 v[2:5], v147
	ds_read_b128 v[6:9], v158 offset:49152
	ds_read_b128 v[10:13], v158 offset:57344
	v_readlane_b32 s36, v254, 26
	s_add_i32 s50, s36, s33
	s_add_i32 s48, s50, -2
	s_waitcnt lgkmcnt(1)
	v_mfma_f32_32x32x16_bf16 v[112:127], v[6:9], v[2:5], 0
	v_readlane_b32 s36, v255, 32
	s_cmp_lt_u32 s48, s36
	v_readlane_b32 s49, v255, 33
	s_cselect_b64 s[36:37], -1, 0
	s_cmp_ge_u32 s48, s49
	s_cselect_b64 s[48:49], -1, 0
	s_or_b64 s[36:37], s[36:37], s[48:49]
	s_waitcnt lgkmcnt(0)
	v_mfma_f32_32x32x16_bf16 v[96:111], v[10:13], v[2:5], 0
	ds_read_b128 v[2:5], v147 offset:1024
	ds_read_b128 v[6:9], v159 offset:49152
	ds_read_b128 v[10:13], v159 offset:57344
	v_readlane_b32 s48, v255, 48
	s_add_i32 s51, s48, s33
	s_add_i32 s48, s51, -2
	v_med3_i32 v0, s48, -7, 7
	s_movk_i32 s48, 0x7c
	v_mul_lo_u32 v0, v0, s48
	s_waitcnt lgkmcnt(1)
	v_mfma_f32_32x32x16_bf16 v[112:127], v[6:9], v[2:5], v[112:127]
	v_readlane_b32 s48, v255, 50
	v_add_u32_e32 v0, 0, v0
	v_readlane_b32 s49, v255, 51
	s_nor_b64 s[48:49], s[48:49], s[36:37]
	v_mov_b32_e32 v14, 0xf149f2ca
	s_waitcnt lgkmcnt(0)
	v_mfma_f32_32x32x16_bf16 v[96:111], v[10:13], v[2:5], v[96:111]
	ds_read_b128 v[2:5], v147 offset:2048
	ds_read_b128 v[6:9], v160 offset:49152
	ds_read_b128 v[10:13], v160 offset:57344
	s_waitcnt lgkmcnt(1)
	v_mfma_f32_32x32x16_bf16 v[112:127], v[6:9], v[2:5], v[112:127]
	s_waitcnt lgkmcnt(0)
	v_mfma_f32_32x32x16_bf16 v[96:111], v[10:13], v[2:5], v[96:111]
	ds_read_b128 v[2:5], v147 offset:3072
	ds_read_b128 v[6:9], v161 offset:49152
	ds_read_b128 v[10:13], v161 offset:57344
	s_waitcnt lgkmcnt(1)
	v_mfma_f32_32x32x16_bf16 v[112:127], v[6:9], v[2:5], v[112:127]
	s_waitcnt lgkmcnt(0)
	v_mfma_f32_32x32x16_bf16 v[96:111], v[10:13], v[2:5], v[96:111]
	ds_read_b128 v[2:5], v147 offset:4096
	ds_read_b128 v[6:9], v176 offset:49152
	ds_read_b128 v[10:13], v176 offset:57344
	s_waitcnt lgkmcnt(1)
	v_mfma_f32_32x32x16_bf16 v[112:127], v[6:9], v[2:5], v[112:127]
	s_waitcnt lgkmcnt(0)
	v_mfma_f32_32x32x16_bf16 v[96:111], v[10:13], v[2:5], v[96:111]
	ds_read_b128 v[2:5], v147 offset:5120
	ds_read_b128 v[6:9], v177 offset:49152
	ds_read_b128 v[10:13], v177 offset:57344
	s_waitcnt lgkmcnt(1)
	v_mfma_f32_32x32x16_bf16 v[112:127], v[6:9], v[2:5], v[112:127]
	s_waitcnt lgkmcnt(0)
	v_mfma_f32_32x32x16_bf16 v[96:111], v[10:13], v[2:5], v[96:111]
	ds_read_b128 v[2:5], v147 offset:6144
	ds_read_b128 v[6:9], v207 offset:49152
	ds_read_b128 v[10:13], v207 offset:57344
	s_waitcnt lgkmcnt(1)
	v_mfma_f32_32x32x16_bf16 v[112:127], v[6:9], v[2:5], v[112:127]
	s_waitcnt lgkmcnt(0)
	v_mfma_f32_32x32x16_bf16 v[96:111], v[10:13], v[2:5], v[96:111]
	ds_read_b128 v[2:5], v147 offset:7168
	ds_read_b128 v[6:9], v208 offset:49152
	ds_read_b128 v[10:13], v208 offset:57344
	s_waitcnt lgkmcnt(1)
	v_mfma_f32_32x32x16_bf16 v[112:127], v[6:9], v[2:5], v[112:127]
	s_waitcnt lgkmcnt(0)
	v_mfma_f32_32x32x16_bf16 v[96:111], v[10:13], v[2:5], v[96:111]
	v_add_u32_e32 v2, 0x10800, v0
	v_mov_b32_e32 v0, 0xf149f2ca
	v_lshl_add_u32 v162, v242, 2, v2
	ds_read_b32 v162, v162 offset:928
	v_lshl_add_u32 v178, v209, 2, v2
	ds_read_b32 v178, v178 offset:928
	v_lshl_add_u32 v179, v210, 2, v2
	ds_read_b32 v179, v179 offset:928
	v_lshl_add_u32 v180, v211, 2, v2
	ds_read_b32 v180, v180 offset:928
	v_lshl_add_u32 v201, v212, 2, v2
	ds_read_b32 v201, v201 offset:928
	v_lshl_add_u32 v202, v213, 2, v2
	ds_read_b32 v202, v202 offset:928
	v_lshl_add_u32 v168, v214, 2, v2
	ds_read_b32 v168, v168 offset:928
	v_lshl_add_u32 v169, v215, 2, v2
	ds_read_b32 v169, v169 offset:928
	v_lshl_add_u32 v170, v216, 2, v2
	ds_read_b32 v170, v170 offset:928
	v_lshl_add_u32 v171, v217, 2, v2
	ds_read_b32 v171, v171 offset:928
	v_lshl_add_u32 v190, v218, 2, v2
	ds_read_b32 v190, v190 offset:928
	v_lshl_add_u32 v191, v219, 2, v2
	ds_read_b32 v191, v191 offset:928
	v_lshl_add_u32 v193, v220, 2, v2
	ds_read_b32 v193, v193 offset:928
	v_lshl_add_u32 v194, v221, 2, v2
	ds_read_b32 v194, v194 offset:928
	v_lshl_add_u32 v195, v222, 2, v2
	ds_read_b32 v195, v195 offset:928
	v_lshl_add_u32 v196, v223, 2, v2
	ds_read_b32 v196, v196 offset:928
	s_waitcnt lgkmcnt(0)
	s_and_saveexec_b64 vcc, s[48:49]
	s_cbranch_execz .LBB0_451
	s_nop 2
	v_fmamk_f32 v14, v162, 0x413504f3, v112
.LBB0_451:
	s_or_b64 exec, exec, vcc
	s_xor_b64 vcc, s[36:37], -1
	s_mov_b64 s[54:55], s[52:53]
	s_and_b64 s[48:49], vcc, s[52:53]
	v_readlane_b32 s52, v255, 52
	v_readlane_b32 s53, v255, 53
	s_and_b64 s[52:53], s[48:49], s[52:53]
	s_and_saveexec_b64 s[48:49], s[52:53]
	s_cbranch_execz .LBB0_453
	v_fmamk_f32 v0, v178, 0x413504f3, v96
.LBB0_453:
	s_or_b64 exec, exec, s[48:49]
	v_readlane_b32 s48, v255, 54
	v_readlane_b32 s49, v255, 55
	s_nor_b64 s[52:53], s[48:49], s[36:37]
	v_mov_b32_e32 v15, 0xf149f2ca
	v_mov_b32_e32 v96, 0xf149f2ca
	s_and_saveexec_b64 s[48:49], s[52:53]
	s_cbranch_execz .LBB0_455
	v_fmamk_f32 v96, v179, 0x413504f3, v113
.LBB0_455:
	s_or_b64 exec, exec, s[48:49]
	v_readlane_b32 s48, v255, 56
	v_readlane_b32 s49, v255, 57
	s_and_b64 s[48:49], vcc, s[48:49]
	s_and_b64 s[52:53], s[48:49], s[56:57]
	s_and_saveexec_b64 s[48:49], s[52:53]
	s_cbranch_execz .LBB0_457
	v_fmamk_f32 v15, v180, 0x413504f3, v97
.LBB0_457:
	s_or_b64 exec, exec, s[48:49]
	s_nor_b64 s[52:53], s[58:59], s[36:37]
	v_mov_b32_e32 v97, 0xf149f2ca
	v_mov_b32_e32 v243, 0xf149f2ca
	s_and_saveexec_b64 s[48:49], s[52:53]
	s_cbranch_execz .LBB0_459
	v_fmamk_f32 v243, v201, 0x413504f3, v114
.LBB0_459:
	s_or_b64 exec, exec, s[48:49]
	s_and_b64 s[48:49], vcc, s[60:61]
	s_and_b64 s[52:53], s[48:49], s[62:63]
	s_and_saveexec_b64 s[48:49], s[52:53]
	s_cbranch_execz .LBB0_461
	v_fmamk_f32 v97, v202, 0x413504f3, v98
; __device__ __forceinline__ int crow(int r, int hi) { return (r & 3) + 8 * (r >> 2) + 4 * hi; }
; __device__ __forceinline__ void na_hook(f32x16& p0, f32x16& p1, int kr, int q_row, int q_col, int win_r, int win_c, const float* rpb, float inv_scale, int hi) {
;   const bool rowok = (kr >= win_r) && (kr < win_r + 8);
;   int ir = kr - q_row + 7; ir = ir < 0 ? 0 : (ir > 14 ? 14 : ir);
;   const float* rp = rpb + ir * 31;
; #pragma unroll
;   for (int r = 0; r < 16; ++r) {
;     const int kc = crow(r, hi);
;     { const bool ok = rowok && kc >= win_c && kc < win_c + 16; int ic = kc - q_col + 15; ic = ic < 0 ? 0 : (ic > 30 ? 30 : ic);
;       p0[r] = ok ? fmaf(rp[ic], inv_scale, p0[r]) : -1e30f; }
;     { const int kc2 = kc + 32; const bool ok = rowok && kc2 >= win_c && kc2 < win_c + 16; int ic = kc2 - q_col + 15; ic = ic < 0 ? 0 : (ic > 30 ? 30 : ic);
;       p1[r] = ok ? fmaf(rp[ic], inv_scale, p1[r]) : -1e30f; }
;   }
; }
.LBB0_461:
	s_or_b64 exec, exec, s[48:49]
	s_nor_b64 s[52:53], s[64:65], s[36:37]
	v_mov_b32_e32 v98, 0xf149f2ca
	v_mov_b32_e32 v244, 0xf149f2ca
	s_and_saveexec_b64 s[48:49], s[52:53]
	s_cbranch_execz .LBB0_463
	v_fmamk_f32 v244, v168, 0x413504f3, v115
.LBB0_463:
	s_or_b64 exec, exec, s[48:49]
	s_and_b64 s[48:49], vcc, s[66:67]
	s_and_b64 s[52:53], s[48:49], s[68:69]
	s_and_saveexec_b64 s[48:49], s[52:53]
	s_cbranch_execz .LBB0_465
	v_fmamk_f32 v98, v169, 0x413504f3, v99
.LBB0_465:
	s_or_b64 exec, exec, s[48:49]
	s_nor_b64 s[52:53], s[70:71], s[36:37]
	v_mov_b32_e32 v99, 0xf149f2ca
	v_mov_b32_e32 v115, 0xf149f2ca
	s_and_saveexec_b64 s[48:49], s[52:53]
	s_cbranch_execz .LBB0_467
	v_fmamk_f32 v115, v170, 0x413504f3, v116
.LBB0_467:
	s_or_b64 exec, exec, s[48:49]
	s_and_b64 s[48:49], vcc, s[72:73]
	s_and_b64 s[52:53], s[48:49], s[74:75]
	s_and_saveexec_b64 s[48:49], s[52:53]
	s_cbranch_execz .LBB0_469
	v_fmamk_f32 v99, v171, 0x413504f3, v100
.LBB0_469:
	s_or_b64 exec, exec, s[48:49]
	s_nor_b64 s[52:53], s[76:77], s[36:37]
	v_mov_b32_e32 v100, 0xf149f2ca
	v_mov_b32_e32 v245, 0xf149f2ca
	s_and_saveexec_b64 s[48:49], s[52:53]
	s_cbranch_execz .LBB0_471
	v_fmamk_f32 v245, v190, 0x413504f3, v117
.LBB0_471:
	s_or_b64 exec, exec, s[48:49]
	s_and_b64 s[48:49], vcc, s[78:79]
	s_and_b64 s[52:53], s[48:49], s[80:81]
	s_and_saveexec_b64 s[48:49], s[52:53]
	s_cbranch_execz .LBB0_473
	v_fmamk_f32 v100, v191, 0x413504f3, v101
.LBB0_473:
	s_or_b64 exec, exec, s[48:49]
	s_nor_b64 s[52:53], s[82:83], s[36:37]
	v_mov_b32_e32 v101, 0xf149f2ca
	v_mov_b32_e32 v117, 0xf149f2ca
	s_and_saveexec_b64 s[48:49], s[52:53]
	s_cbranch_execz .LBB0_475
	v_fmamk_f32 v117, v193, 0x413504f3, v118
.LBB0_475:
	s_or_b64 exec, exec, s[48:49]
	s_and_b64 s[48:49], vcc, s[84:85]
	s_and_b64 s[52:53], s[48:49], s[86:87]
	s_and_saveexec_b64 s[48:49], s[52:53]
	s_cbranch_execz .LBB0_477
	v_fmamk_f32 v101, v194, 0x413504f3, v102
.LBB0_477:
	s_or_b64 exec, exec, s[48:49]
	s_nor_b64 s[52:53], s[88:89], s[36:37]
	v_mov_b32_e32 v102, 0xf149f2ca
	v_mov_b32_e32 v118, 0xf149f2ca
	s_and_saveexec_b64 s[48:49], s[52:53]
	s_cbranch_execz .LBB0_479
	v_fmamk_f32 v118, v195, 0x413504f3, v119
.LBB0_479:
	s_or_b64 exec, exec, s[48:49]
	s_and_b64 s[48:49], vcc, s[90:91]
	s_and_b64 s[52:53], s[48:49], s[92:93]
	s_and_saveexec_b64 s[48:49], s[52:53]
	s_cbranch_execz .LBB0_481
	v_fmamk_f32 v102, v196, 0x413504f3, v103
.LBB0_481:
	s_or_b64 exec, exec, s[48:49]
	v_lshl_add_u32 v162, v224, 2, v2
	ds_read_b32 v162, v162 offset:928
	v_lshl_add_u32 v178, v225, 2, v2
	ds_read_b32 v178, v178 offset:928
	v_lshl_add_u32 v179, v226, 2, v2
	ds_read_b32 v179, v179 offset:928
	v_lshl_add_u32 v180, v227, 2, v2
	ds_read_b32 v180, v180 offset:928
	v_lshl_add_u32 v201, v228, 2, v2
	ds_read_b32 v201, v201 offset:928
	v_lshl_add_u32 v202, v229, 2, v2
	ds_read_b32 v202, v202 offset:928
	v_lshl_add_u32 v168, v230, 2, v2
	ds_read_b32 v168, v168 offset:928
	v_lshl_add_u32 v169, v231, 2, v2
	ds_read_b32 v169, v169 offset:928
	v_lshl_add_u32 v170, v232, 2, v2
	ds_read_b32 v170, v170 offset:928
	v_lshl_add_u32 v171, v241, 2, v2
	ds_read_b32 v171, v171 offset:1152
	v_lshl_add_u32 v190, v233, 2, v2
	ds_read_b32 v190, v190 offset:928
	v_lshl_add_u32 v191, v240, 2, v2
	ds_read_b32 v191, v191 offset:1156
	v_lshl_add_u32 v193, v234, 2, v2
	ds_read_b32 v193, v193 offset:928
	v_lshl_add_u32 v194, v238, 2, v2
	ds_read_b32 v194, v194 offset:1160
	v_lshl_add_u32 v195, v235, 2, v2
	ds_read_b32 v195, v195 offset:928
	v_lshl_add_u32 v196, v236, 2, v2
	ds_read_b32 v196, v196 offset:1164
	s_nor_b64 s[52:53], s[46:47], s[36:37]
	v_mov_b32_e32 v103, 0xf149f2ca
	v_mov_b32_e32 v119, 0xf149f2ca
	s_waitcnt lgkmcnt(0)
	s_and_saveexec_b64 s[48:49], s[52:53]
	s_cbranch_execz .LBB0_483
	v_fmamk_f32 v119, v162, 0x413504f3, v120
; __device__ __forceinline__ int crow(int r, int hi) { return (r & 3) + 8 * (r >> 2) + 4 * hi; }
; __device__ __forceinline__ void na_hook(f32x16& p0, f32x16& p1, int kr, int q_row, int q_col, int win_r, int win_c, const float* rpb, float inv_scale, int hi) {
;   const bool rowok = (kr >= win_r) && (kr < win_r + 8);
;   int ir = kr - q_row + 7; ir = ir < 0 ? 0 : (ir > 14 ? 14 : ir);
;   const float* rp = rpb + ir * 31;
; #pragma unroll
;   for (int r = 0; r < 16; ++r) {
;     const int kc = crow(r, hi);
;     { const bool ok = rowok && kc >= win_c && kc < win_c + 16; int ic = kc - q_col + 15; ic = ic < 0 ? 0 : (ic > 30 ? 30 : ic);
;       p0[r] = ok ? fmaf(rp[ic], inv_scale, p0[r]) : -1e30f; }
;     { const int kc2 = kc + 32; const bool ok = rowok && kc2 >= win_c && kc2 < win_c + 16; int ic = kc2 - q_col + 15; ic = ic < 0 ? 0 : (ic > 30 ? 30 : ic);
;       p1[r] = ok ? fmaf(rp[ic], inv_scale, p1[r]) : -1e30f; }
;   }
; }
.LBB0_483:
	s_or_b64 exec, exec, s[48:49]
	s_and_b64 s[52:53], vcc, s[94:95]
	s_and_saveexec_b64 s[48:49], s[52:53]
	s_cbranch_execz .LBB0_485
	v_fmamk_f32 v103, v178, 0x413504f3, v104
.LBB0_485:
	s_or_b64 exec, exec, s[48:49]
	s_or_b64 s[48:49], s[96:97], s[36:37]
	s_nor_b64 s[52:53], s[48:49], s[2:3]
	v_mov_b32_e32 v104, 0xf149f2ca
	v_mov_b32_e32 v120, 0xf149f2ca
	s_and_saveexec_b64 s[48:49], s[52:53]
	s_cbranch_execz .LBB0_487
	v_fmamk_f32 v120, v179, 0x413504f3, v121
.LBB0_487:
	s_or_b64 exec, exec, s[48:49]
	s_and_b64 s[52:53], vcc, s[4:5]
	s_and_saveexec_b64 s[48:49], s[52:53]
	s_cbranch_execz .LBB0_489
	v_fmamk_f32 v104, v180, 0x413504f3, v105
.LBB0_489:
	s_or_b64 exec, exec, s[48:49]
	s_or_b64 s[48:49], s[6:7], s[36:37]
	s_nor_b64 s[52:53], s[48:49], s[8:9]
	v_mov_b32_e32 v105, 0xf149f2ca
	v_mov_b32_e32 v121, 0xf149f2ca
	s_and_saveexec_b64 s[48:49], s[52:53]
	s_cbranch_execz .LBB0_491
	v_fmamk_f32 v121, v201, 0x413504f3, v122
.LBB0_491:
	s_or_b64 exec, exec, s[48:49]
	s_and_b64 s[52:53], vcc, s[10:11]
	s_and_saveexec_b64 s[48:49], s[52:53]
	s_cbranch_execz .LBB0_493
	v_fmamk_f32 v105, v202, 0x413504f3, v106
.LBB0_493:
	s_or_b64 exec, exec, s[48:49]
	s_or_b64 s[48:49], s[12:13], s[36:37]
	s_nor_b64 s[52:53], s[48:49], s[14:15]
	v_mov_b32_e32 v106, 0xf149f2ca
	v_mov_b32_e32 v122, 0xf149f2ca
	s_and_saveexec_b64 s[48:49], s[52:53]
	s_cbranch_execz .LBB0_495
	v_fmamk_f32 v122, v168, 0x413504f3, v123
.LBB0_495:
	s_or_b64 exec, exec, s[48:49]
	s_and_b64 s[52:53], vcc, s[16:17]
	s_and_saveexec_b64 s[48:49], s[52:53]
	s_cbranch_execz .LBB0_497
	v_fmamk_f32 v106, v169, 0x413504f3, v107
.LBB0_497:
	s_or_b64 exec, exec, s[48:49]
	s_or_b64 s[48:49], s[18:19], s[36:37]
	s_nor_b64 s[52:53], s[48:49], s[20:21]
	v_mov_b32_e32 v107, 0xf149f2ca
	v_mov_b32_e32 v123, 0xf149f2ca
	s_and_saveexec_b64 s[48:49], s[52:53]
	s_cbranch_execz .LBB0_499
	v_fmamk_f32 v123, v170, 0x413504f3, v124
.LBB0_499:
	s_or_b64 exec, exec, s[48:49]
	s_nor_b64 s[52:53], s[36:37], s[22:23]
	s_and_saveexec_b64 s[48:49], s[52:53]
	s_cbranch_execz .LBB0_501
	v_fmamk_f32 v107, v171, 0x413504f3, v108
.LBB0_501:
	s_or_b64 exec, exec, s[48:49]
	s_or_b64 s[48:49], s[24:25], s[36:37]
	s_nor_b64 s[52:53], s[48:49], s[26:27]
	v_mov_b32_e32 v108, 0xf149f2ca
	v_mov_b32_e32 v124, 0xf149f2ca
	s_and_saveexec_b64 s[48:49], s[52:53]
	s_cbranch_execz .LBB0_503
	v_fmamk_f32 v124, v190, 0x413504f3, v125
.LBB0_503:
	s_or_b64 exec, exec, s[48:49]
	s_nor_b64 s[52:53], s[36:37], s[28:29]
	s_and_saveexec_b64 s[48:49], s[52:53]
	s_cbranch_execz .LBB0_505
	v_fmamk_f32 v108, v191, 0x413504f3, v109
.LBB0_505:
	s_or_b64 exec, exec, s[48:49]
	s_or_b64 s[48:49], s[30:31], s[36:37]
	s_nor_b64 s[52:53], s[48:49], s[34:35]
	v_mov_b32_e32 v109, 0xf149f2ca
	v_mov_b32_e32 v125, 0xf149f2ca
	s_and_saveexec_b64 s[48:49], s[52:53]
	s_cbranch_execz .LBB0_507
	v_fmamk_f32 v125, v193, 0x413504f3, v126
.LBB0_507:
	s_or_b64 exec, exec, s[48:49]
	s_nor_b64 s[52:53], s[36:37], s[42:43]
	s_and_saveexec_b64 s[48:49], s[52:53]
	s_cbranch_execz .LBB0_509
	v_fmamk_f32 v109, v194, 0x413504f3, v110
.LBB0_509:
	s_or_b64 exec, exec, s[48:49]
	s_or_b64 s[48:49], s[0:1], s[36:37]
	s_nor_b64 s[48:49], s[48:49], s[40:41]
	v_mov_b32_e32 v110, 0xf149f2ca
	v_mov_b32_e32 v126, 0xf149f2ca
	s_and_saveexec_b64 vcc, s[48:49]
	s_cbranch_execz .LBB0_511
	v_fmac_f32_e32 v127, 0x413504f3, v195
	v_mov_b32_e32 v126, v127
.LBB0_511:
	s_or_b64 exec, exec, vcc
	s_nor_b64 s[48:49], s[36:37], s[38:39]
	s_and_saveexec_b64 s[36:37], s[48:49]
	s_cbranch_execz .LBB0_513
	v_fmac_f32_e32 v111, 0x413504f3, v196
	v_mov_b32_e32 v110, v111

; __device__ __forceinline__ int crow(int r, int hi) { return (r & 3) + 8 * (r >> 2) + 4 * hi; }
; __device__ __forceinline__ void partialSM(f32x16& p0, f32x16& p1, float& m_reg, float& mn, float& alpha, float C, float thrRaw) {
;     ...
;   float mnC = -mn * C;
; #pragma unroll
;   for (int r = 0; r < 16; ++r) p0[r] = fmaf(p0[r], C, mnC);
; #pragma unroll
;   for (int r = 0; r < 16; ++r) p1[r] = fmaf(p1[r], C, mnC);
; #pragma unroll
;   for (int r = 0; r < 16; ++r) p0[r] = __builtin_amdgcn_exp2f(p0[r]);
; template <int DK, bool QL>
; __device__ __forceinline__ void qkt(f32x16& p0, f32x16& p1, const bf16* Ks, const bf16x8* qr, const char* ql, int r32, int hi) {
;   p0 = f32x16{}; p1 = f32x16{};
; #pragma unroll
;   for (int d0 = 0; d0 < DK / 16; ++d0) { int cb = (d0 * 16 + hi * 8) * 2;
;     const bf16x8 qv = QL ? *reinterpret_cast<const bf16x8*>(ql + d0 * 1024) : qr[d0];
;     bf16x8 b0 = *reinterpret_cast<const bf16x8*>((const char*)Ks + kswz<DK>(r32, cb));
;     bf16x8 b1 = *reinterpret_cast<const bf16x8*>((const char*)Ks + kswz<DK>(32 + r32, cb));
;     p0 = __builtin_amdgcn_mfma_f32_32x32x16_bf16(b0, qv, p0, 0, 0, 0);
;     p1 = __builtin_amdgcn_mfma_f32_32x32x16_bf16(b1, qv, p1, 0, 0, 0); }
; }
; __device__ __forceinline__ void na_hook(f32x16& p0, f32x16& p1, int kr, int q_row, int q_col, int win_r, int win_c, const float* rpb, float inv_scale, int hi) {
;   const bool rowok = (kr >= win_r) && (kr < win_r + 8);
;   int ir = kr - q_row + 7; ir = ir < 0 ? 0 : (ir > 14 ? 14 : ir);
;   const float* rp = rpb + ir * 31;
; #pragma unroll
;   for (int r = 0; r < 16; ++r) {
;     const int kc = crow(r, hi);
;     { const bool ok = rowok && kc >= win_c && kc < win_c + 16; int ic = kc - q_col + 15; ic = ic < 0 ? 0 : (ic > 30 ? 30 : ic);
;       p0[r] = ok ? fmaf(rp[ic], inv_scale, p0[r]) : -1e30f; }
;     { const int kc2 = kc + 32; const bool ok = rowok && kc2 >= win_c && kc2 < win_c + 16; int ic = kc2 - q_col + 15; ic = ic < 0 ? 0 : (ic > 30 ? 30 : ic);
;       p1[r] = ok ? fmaf(rp[ic], inv_scale, p1[r]) : -1e30f; }
;   }
; }
.LBB0_517:
	v_cndmask_b32_e64 v116, v2, v237, s[36:37]
	v_mul_f32_e32 v127, 0xbe0293ee, v116
	v_fmamk_f32 v2, v14, 0x3e0293ee, v127
	v_fmamk_f32 v3, v96, 0x3e0293ee, v127
	v_fmamk_f32 v4, v243, 0x3e0293ee, v127
	v_fmamk_f32 v5, v244, 0x3e0293ee, v127
	v_fmamk_f32 v6, v115, 0x3e0293ee, v127
	v_fmamk_f32 v7, v245, 0x3e0293ee, v127
	v_fmamk_f32 v8, v117, 0x3e0293ee, v127
	v_fmamk_f32 v11, v118, 0x3e0293ee, v127
	v_fmamk_f32 v14, v119, 0x3e0293ee, v127
	v_fmamk_f32 v80, v120, 0x3e0293ee, v127
	v_fmamk_f32 v81, v121, 0x3e0293ee, v127
	v_fmamk_f32 v82, v122, 0x3e0293ee, v127
	v_fmamk_f32 v83, v123, 0x3e0293ee, v127
	v_fmamk_f32 v84, v124, 0x3e0293ee, v127
	v_fmamk_f32 v85, v125, 0x3e0293ee, v127
	v_fmamk_f32 v86, v126, 0x3e0293ee, v127
	v_fmamk_f32 v124, v0, 0x3e0293ee, v127
	v_exp_f32_e32 v121, v2
	v_exp_f32_e32 v123, v3
	v_exp_f32_e32 v12, v4
	v_exp_f32_e32 v122, v5
	v_exp_f32_e32 v10, v6
	v_exp_f32_e32 v13, v7
	v_exp_f32_e32 v9, v8
	v_exp_f32_e32 v11, v11
	v_exp_f32_e32 v6, v14
	v_exp_f32_e32 v8, v80
	v_exp_f32_e32 v4, v81
	v_exp_f32_e32 v7, v82
	v_exp_f32_e32 v2, v83
	v_exp_f32_e32 v5, v84
	v_exp_f32_e32 v0, v85
	v_exp_f32_e32 v3, v86
	v_fmamk_f32 v125, v15, 0x3e0293ee, v127
	v_fmamk_f32 v126, v97, 0x3e0293ee, v127
	v_fmamk_f32 v130, v98, 0x3e0293ee, v127
	v_fmamk_f32 v131, v99, 0x3e0293ee, v127
	v_fmamk_f32 v132, v100, 0x3e0293ee, v127
	v_fmamk_f32 v133, v101, 0x3e0293ee, v127
	v_fmamk_f32 v134, v102, 0x3e0293ee, v127
	v_fmamk_f32 v135, v103, 0x3e0293ee, v127
	v_fmamk_f32 v136, v104, 0x3e0293ee, v127
	v_fmamk_f32 v137, v105, 0x3e0293ee, v127
	v_fmamk_f32 v138, v106, 0x3e0293ee, v127
	v_fmamk_f32 v139, v107, 0x3e0293ee, v127
	v_fmamk_f32 v140, v108, 0x3e0293ee, v127
	v_fmamk_f32 v141, v109, 0x3e0293ee, v127
	v_fmac_f32_e32 v127, 0x3e0293ee, v110
	s_mov_b64 s[52:53], s[54:55]
	s_waitcnt lgkmcnt(0)
	s_barrier
	ds_read_b128 v[80:83], v147
	ds_read_b128 v[84:87], v158 offset:32768
	ds_read_b128 v[88:91], v158 offset:40960
	ds_read_b128 v[142:145], v147 offset:1024
	ds_read_b128 v[244:247], v159 offset:32768
	ds_read_b128 v[164:167], v159 offset:40960
	s_add_i32 s50, s50, -1
	v_readlane_b32 s36, v255, 32
	s_waitcnt lgkmcnt(4)
	v_mfma_f32_32x32x16_bf16 v[96:111], v[84:87], v[80:83], 0
	s_cmp_lt_u32 s50, s36
	v_readlane_b32 s48, v255, 33
	s_cselect_b64 s[36:37], -1, 0
	s_cmp_ge_u32 s50, s48
	s_cselect_b64 s[48:49], -1, 0
	s_add_i32 s51, s51, -1
	s_or_b64 s[36:37], s[36:37], s[48:49]
	s_waitcnt lgkmcnt(3)
	v_mfma_f32_32x32x16_bf16 v[80:95], v[88:91], v[80:83], 0
	v_med3_i32 v14, s51, -7, 7
	s_movk_i32 s48, 0x7c
	v_mul_lo_u32 v14, v14, s48
	v_readlane_b32 s48, v255, 50
	v_add_u32_e32 v14, 0, v14
	v_readlane_b32 s49, v255, 51
	s_nor_b64 s[50:51], s[48:49], s[36:37]
	s_waitcnt lgkmcnt(1)
	v_mfma_f32_32x32x16_bf16 v[96:111], v[244:247], v[142:145], v[96:111]
	v_mov_b32_e32 v115, 0xf149f2ca
	s_waitcnt lgkmcnt(0)
	v_mfma_f32_32x32x16_bf16 v[80:95], v[164:167], v[142:145], v[80:95]
	ds_read_b128 v[142:145], v147 offset:2048
	ds_read_b128 v[164:167], v160 offset:32768
	ds_read_b128 v[244:247], v160 offset:40960
	s_waitcnt lgkmcnt(1)
	v_mfma_f32_32x32x16_bf16 v[96:111], v[164:167], v[142:145], v[96:111]
	s_waitcnt lgkmcnt(0)
	v_mfma_f32_32x32x16_bf16 v[80:95], v[244:247], v[142:145], v[80:95]
	ds_read_b128 v[142:145], v147 offset:3072
	ds_read_b128 v[164:167], v161 offset:32768
	ds_read_b128 v[244:247], v161 offset:40960
	s_waitcnt lgkmcnt(1)
	v_mfma_f32_32x32x16_bf16 v[96:111], v[164:167], v[142:145], v[96:111]
	s_waitcnt lgkmcnt(0)
	v_mfma_f32_32x32x16_bf16 v[80:95], v[244:247], v[142:145], v[80:95]
	ds_read_b128 v[142:145], v147 offset:4096
	ds_read_b128 v[164:167], v176 offset:32768
	ds_read_b128 v[244:247], v176 offset:40960
	s_waitcnt lgkmcnt(1)
	v_mfma_f32_32x32x16_bf16 v[96:111], v[164:167], v[142:145], v[96:111]
	s_waitcnt lgkmcnt(0)
	v_mfma_f32_32x32x16_bf16 v[80:95], v[244:247], v[142:145], v[80:95]
	ds_read_b128 v[142:145], v147 offset:5120
	ds_read_b128 v[164:167], v177 offset:32768
	ds_read_b128 v[244:247], v177 offset:40960
	s_waitcnt lgkmcnt(1)
	v_mfma_f32_32x32x16_bf16 v[96:111], v[164:167], v[142:145], v[96:111]
	s_waitcnt lgkmcnt(0)
	v_mfma_f32_32x32x16_bf16 v[80:95], v[244:247], v[142:145], v[80:95]
	ds_read_b128 v[142:145], v147 offset:6144
	ds_read_b128 v[164:167], v207 offset:32768
	ds_read_b128 v[244:247], v207 offset:40960
	s_waitcnt lgkmcnt(1)
	v_mfma_f32_32x32x16_bf16 v[96:111], v[164:167], v[142:145], v[96:111]
	s_waitcnt lgkmcnt(0)
	v_mfma_f32_32x32x16_bf16 v[80:95], v[244:247], v[142:145], v[80:95]
	ds_read_b128 v[142:145], v147 offset:7168
	ds_read_b128 v[164:167], v208 offset:32768
	ds_read_b128 v[244:247], v208 offset:40960
	s_waitcnt lgkmcnt(1)
	v_mfma_f32_32x32x16_bf16 v[96:111], v[164:167], v[142:145], v[96:111]
	s_waitcnt lgkmcnt(0)
	v_mfma_f32_32x32x16_bf16 v[80:95], v[244:247], v[142:145], v[80:95]
	v_add_u32_e32 v142, 0x10800, v14
	v_mov_b32_e32 v14, 0xf149f2ca
	v_lshl_add_u32 v162, v242, 2, v142
	ds_read_b32 v162, v162 offset:928
	v_lshl_add_u32 v178, v209, 2, v142
	ds_read_b32 v178, v178 offset:928
	v_lshl_add_u32 v179, v210, 2, v142
	ds_read_b32 v179, v179 offset:928
	v_lshl_add_u32 v180, v211, 2, v142
	ds_read_b32 v180, v180 offset:928
	v_lshl_add_u32 v201, v212, 2, v142
	ds_read_b32 v201, v201 offset:928
	v_lshl_add_u32 v202, v213, 2, v142
	ds_read_b32 v202, v202 offset:928
	v_lshl_add_u32 v168, v214, 2, v142
	ds_read_b32 v168, v168 offset:928
	v_lshl_add_u32 v169, v215, 2, v142
	ds_read_b32 v169, v169 offset:928
	v_lshl_add_u32 v170, v216, 2, v142
	ds_read_b32 v170, v170 offset:928
	v_lshl_add_u32 v171, v217, 2, v142
	ds_read_b32 v171, v171 offset:928
	v_lshl_add_u32 v190, v218, 2, v142
	ds_read_b32 v190, v190 offset:928
	v_lshl_add_u32 v191, v219, 2, v142
	ds_read_b32 v191, v191 offset:928
	v_lshl_add_u32 v193, v220, 2, v142
	ds_read_b32 v193, v193 offset:928
	v_lshl_add_u32 v194, v221, 2, v142
	ds_read_b32 v194, v194 offset:928
	v_lshl_add_u32 v195, v222, 2, v142
	ds_read_b32 v195, v195 offset:928
	v_lshl_add_u32 v196, v223, 2, v142
	ds_read_b32 v196, v196 offset:928
	s_waitcnt lgkmcnt(0)
	s_and_saveexec_b64 s[48:49], s[50:51]
	s_cbranch_execz .LBB0_519
	s_nop 2
	v_fmamk_f32 v115, v162, 0x413504f3, v96
; __device__ __forceinline__ int crow(int r, int hi) { return (r & 3) + 8 * (r >> 2) + 4 * hi; }
; __device__ __forceinline__ void na_hook(f32x16& p0, f32x16& p1, int kr, int q_row, int q_col, int win_r, int win_c, const float* rpb, float inv_scale, int hi) {
;   const bool rowok = (kr >= win_r) && (kr < win_r + 8);
;   int ir = kr - q_row + 7; ir = ir < 0 ? 0 : (ir > 14 ? 14 : ir);
;   const float* rp = rpb + ir * 31;
; #pragma unroll
;   for (int r = 0; r < 16; ++r) {
;     const int kc = crow(r, hi);
;     { const bool ok = rowok && kc >= win_c && kc < win_c + 16; int ic = kc - q_col + 15; ic = ic < 0 ? 0 : (ic > 30 ? 30 : ic);
;       p0[r] = ok ? fmaf(rp[ic], inv_scale, p0[r]) : -1e30f; }
;     { const int kc2 = kc + 32; const bool ok = rowok && kc2 >= win_c && kc2 < win_c + 16; int ic = kc2 - q_col + 15; ic = ic < 0 ? 0 : (ic > 30 ? 30 : ic);
;       p1[r] = ok ? fmaf(rp[ic], inv_scale, p1[r]) : -1e30f; }
;   }
; }
.LBB0_519:
	s_or_b64 exec, exec, s[48:49]
	s_xor_b64 vcc, s[36:37], -1
	v_readlane_b32 s50, v255, 52
	s_and_b64 s[48:49], vcc, s[52:53]
	v_readlane_b32 s51, v255, 53
	s_and_b64 s[50:51], s[48:49], s[50:51]
	s_and_saveexec_b64 s[48:49], s[50:51]
	s_cbranch_execz .LBB0_521
	v_fmamk_f32 v14, v178, 0x413504f3, v80
.LBB0_521:
	s_or_b64 exec, exec, s[48:49]
	v_readlane_b32 s48, v255, 54
	v_readlane_b32 s49, v255, 55
	s_nor_b64 s[50:51], s[48:49], s[36:37]
	v_mov_b32_e32 v15, 0xf149f2ca
	v_mov_b32_e32 v117, 0xf149f2ca
	s_and_saveexec_b64 s[48:49], s[50:51]
	s_cbranch_execz .LBB0_523
	v_fmamk_f32 v117, v179, 0x413504f3, v97
.LBB0_523:
	s_or_b64 exec, exec, s[48:49]
	v_readlane_b32 s48, v255, 56
	v_readlane_b32 s49, v255, 57
	s_and_b64 s[48:49], vcc, s[48:49]
	s_and_b64 s[50:51], s[48:49], s[56:57]
	s_and_saveexec_b64 s[48:49], s[50:51]
	s_cbranch_execz .LBB0_525
	v_fmamk_f32 v15, v180, 0x413504f3, v81
.LBB0_525:
	s_or_b64 exec, exec, s[48:49]
	s_nor_b64 s[50:51], s[58:59], s[36:37]
	v_mov_b32_e32 v96, 0xf149f2ca
	v_mov_b32_e32 v118, 0xf149f2ca
	s_and_saveexec_b64 s[48:49], s[50:51]
	s_cbranch_execz .LBB0_527
	v_fmamk_f32 v118, v201, 0x413504f3, v98
.LBB0_527:
	s_or_b64 exec, exec, s[48:49]
	s_and_b64 s[48:49], vcc, s[60:61]
	s_and_b64 s[50:51], s[48:49], s[62:63]
	s_and_saveexec_b64 s[48:49], s[50:51]
	s_cbranch_execz .LBB0_529
	v_fmamk_f32 v96, v202, 0x413504f3, v82
.LBB0_529:
	s_or_b64 exec, exec, s[48:49]
	s_nor_b64 s[50:51], s[64:65], s[36:37]
	v_mov_b32_e32 v97, 0xf149f2ca
	v_mov_b32_e32 v119, 0xf149f2ca
	s_and_saveexec_b64 s[48:49], s[50:51]
	s_cbranch_execz .LBB0_531
	v_fmamk_f32 v119, v168, 0x413504f3, v99
.LBB0_531:
	s_or_b64 exec, exec, s[48:49]
	s_and_b64 s[48:49], vcc, s[66:67]
	s_and_b64 s[50:51], s[48:49], s[68:69]
	s_and_saveexec_b64 s[48:49], s[50:51]
	s_cbranch_execz .LBB0_533
	v_fmamk_f32 v97, v169, 0x413504f3, v83
.LBB0_533:
	s_or_b64 exec, exec, s[48:49]
	s_nor_b64 s[50:51], s[70:71], s[36:37]
	v_mov_b32_e32 v98, 0xf149f2ca
	v_mov_b32_e32 v120, 0xf149f2ca
	s_and_saveexec_b64 s[48:49], s[50:51]
	s_cbranch_execz .LBB0_535
	v_fmamk_f32 v120, v170, 0x413504f3, v100
.LBB0_535:
	s_or_b64 exec, exec, s[48:49]
	s_and_b64 s[48:49], vcc, s[72:73]
	s_and_b64 s[50:51], s[48:49], s[74:75]
	s_and_saveexec_b64 s[48:49], s[50:51]
	s_cbranch_execz .LBB0_537
	v_fmamk_f32 v98, v171, 0x413504f3, v84
.LBB0_537:
	s_or_b64 exec, exec, s[48:49]
	s_nor_b64 s[50:51], s[76:77], s[36:37]
	v_mov_b32_e32 v99, 0xf149f2ca
	v_mov_b32_e32 v100, 0xf149f2ca
	s_and_saveexec_b64 s[48:49], s[50:51]
	s_cbranch_execz .LBB0_539
	v_fmamk_f32 v100, v190, 0x413504f3, v101
.LBB0_539:
	s_or_b64 exec, exec, s[48:49]
	s_and_b64 s[48:49], vcc, s[78:79]
	s_and_b64 s[50:51], s[48:49], s[80:81]
	s_and_saveexec_b64 s[48:49], s[50:51]
	s_cbranch_execz .LBB0_541
	v_fmamk_f32 v99, v191, 0x413504f3, v85
.LBB0_541:
	s_or_b64 exec, exec, s[48:49]
	s_nor_b64 s[50:51], s[82:83], s[36:37]
	v_mov_b32_e32 v84, 0xf149f2ca
	v_mov_b32_e32 v101, 0xf149f2ca
	s_and_saveexec_b64 s[48:49], s[50:51]
	s_cbranch_execz .LBB0_543
	v_fmamk_f32 v101, v193, 0x413504f3, v102
.LBB0_543:
	s_or_b64 exec, exec, s[48:49]
	s_and_b64 s[48:49], vcc, s[84:85]
	s_and_b64 s[50:51], s[48:49], s[86:87]
	s_and_saveexec_b64 s[48:49], s[50:51]
	s_cbranch_execz .LBB0_545
	v_fmamk_f32 v84, v194, 0x413504f3, v86
.LBB0_545:
	s_or_b64 exec, exec, s[48:49]
	s_nor_b64 s[50:51], s[88:89], s[36:37]
	v_mov_b32_e32 v85, 0xf149f2ca
	v_mov_b32_e32 v102, 0xf149f2ca
	s_and_saveexec_b64 s[48:49], s[50:51]
	s_cbranch_execz .LBB0_547
	v_fmamk_f32 v102, v195, 0x413504f3, v103
.LBB0_547:
	s_or_b64 exec, exec, s[48:49]
	s_and_b64 s[48:49], vcc, s[90:91]
	s_and_b64 s[50:51], s[48:49], s[92:93]
	s_and_saveexec_b64 s[48:49], s[50:51]
	s_cbranch_execz .LBB0_549
	v_fmamk_f32 v85, v196, 0x413504f3, v87
; __device__ __forceinline__ int crow(int r, int hi) { return (r & 3) + 8 * (r >> 2) + 4 * hi; }
; __device__ __forceinline__ void na_hook(f32x16& p0, f32x16& p1, int kr, int q_row, int q_col, int win_r, int win_c, const float* rpb, float inv_scale, int hi) {
;   const bool rowok = (kr >= win_r) && (kr < win_r + 8);
;   int ir = kr - q_row + 7; ir = ir < 0 ? 0 : (ir > 14 ? 14 : ir);
;   const float* rp = rpb + ir * 31;
; #pragma unroll
;   for (int r = 0; r < 16; ++r) {
;     const int kc = crow(r, hi);
;     { const bool ok = rowok && kc >= win_c && kc < win_c + 16; int ic = kc - q_col + 15; ic = ic < 0 ? 0 : (ic > 30 ? 30 : ic);
;       p0[r] = ok ? fmaf(rp[ic], inv_scale, p0[r]) : -1e30f; }
;     { const int kc2 = kc + 32; const bool ok = rowok && kc2 >= win_c && kc2 < win_c + 16; int ic = kc2 - q_col + 15; ic = ic < 0 ? 0 : (ic > 30 ? 30 : ic);
;       p1[r] = ok ? fmaf(rp[ic], inv_scale, p1[r]) : -1e30f; }
;   }
; }
.LBB0_549:
	s_or_b64 exec, exec, s[48:49]
	v_lshl_add_u32 v162, v224, 2, v142
	ds_read_b32 v162, v162 offset:928
	v_lshl_add_u32 v178, v225, 2, v142
	ds_read_b32 v178, v178 offset:928
	v_lshl_add_u32 v179, v226, 2, v142
	ds_read_b32 v179, v179 offset:928
	v_lshl_add_u32 v180, v227, 2, v142
	ds_read_b32 v180, v180 offset:928
	v_lshl_add_u32 v201, v228, 2, v142
	ds_read_b32 v201, v201 offset:928
	v_lshl_add_u32 v202, v229, 2, v142
	ds_read_b32 v202, v202 offset:928
	v_lshl_add_u32 v168, v230, 2, v142
	ds_read_b32 v168, v168 offset:928
	v_lshl_add_u32 v169, v231, 2, v142
	ds_read_b32 v169, v169 offset:928
	v_lshl_add_u32 v170, v232, 2, v142
	ds_read_b32 v170, v170 offset:928
	v_lshl_add_u32 v171, v241, 2, v142
	ds_read_b32 v171, v171 offset:1152
	v_lshl_add_u32 v190, v233, 2, v142
	ds_read_b32 v190, v190 offset:928
	v_lshl_add_u32 v191, v240, 2, v142
	ds_read_b32 v191, v191 offset:1156
	v_lshl_add_u32 v193, v234, 2, v142
	ds_read_b32 v193, v193 offset:928
	v_lshl_add_u32 v194, v238, 2, v142
	ds_read_b32 v194, v194 offset:1160
	v_lshl_add_u32 v195, v235, 2, v142
	ds_read_b32 v195, v195 offset:928
	v_lshl_add_u32 v196, v236, 2, v142
	ds_read_b32 v196, v196 offset:1164
	s_nor_b64 s[50:51], s[46:47], s[36:37]
	v_mov_b32_e32 v86, 0xf149f2ca
	v_mov_b32_e32 v103, 0xf149f2ca
	s_waitcnt lgkmcnt(0)
	s_and_saveexec_b64 s[48:49], s[50:51]
	s_cbranch_execz .LBB0_551
	v_fmamk_f32 v103, v162, 0x413504f3, v104
.LBB0_551:
	s_or_b64 exec, exec, s[48:49]
	s_and_b64 s[50:51], vcc, s[94:95]
	s_and_saveexec_b64 s[48:49], s[50:51]
	s_cbranch_execz .LBB0_553
	v_fmamk_f32 v86, v178, 0x413504f3, v88
.LBB0_553:
	s_or_b64 exec, exec, s[48:49]
	s_or_b64 s[48:49], s[96:97], s[36:37]
	s_nor_b64 s[50:51], s[48:49], s[2:3]
	v_mov_b32_e32 v87, 0xf149f2ca
	v_mov_b32_e32 v104, 0xf149f2ca
	s_and_saveexec_b64 s[48:49], s[50:51]
	s_cbranch_execz .LBB0_555
	v_fmamk_f32 v104, v179, 0x413504f3, v105
.LBB0_555:
	s_or_b64 exec, exec, s[48:49]
	s_and_b64 s[50:51], vcc, s[4:5]
	s_and_saveexec_b64 s[48:49], s[50:51]
	s_cbranch_execz .LBB0_557
	v_fmamk_f32 v87, v180, 0x413504f3, v89
.LBB0_557:
	s_or_b64 exec, exec, s[48:49]
	s_or_b64 s[48:49], s[6:7], s[36:37]
	s_nor_b64 s[50:51], s[48:49], s[8:9]
	v_mov_b32_e32 v88, 0xf149f2ca
	v_mov_b32_e32 v105, 0xf149f2ca
	s_and_saveexec_b64 s[48:49], s[50:51]
	s_cbranch_execz .LBB0_559
	v_fmamk_f32 v105, v201, 0x413504f3, v106
.LBB0_559:
	s_or_b64 exec, exec, s[48:49]
	s_and_b64 s[50:51], vcc, s[10:11]
	s_and_saveexec_b64 s[48:49], s[50:51]
	s_cbranch_execz .LBB0_561
	v_fmamk_f32 v88, v202, 0x413504f3, v90
.LBB0_561:
	s_or_b64 exec, exec, s[48:49]
	s_or_b64 s[48:49], s[12:13], s[36:37]
	s_nor_b64 s[50:51], s[48:49], s[14:15]
	v_mov_b32_e32 v89, 0xf149f2ca
	v_mov_b32_e32 v106, 0xf149f2ca
	s_and_saveexec_b64 s[48:49], s[50:51]
	s_cbranch_execz .LBB0_563
	v_fmamk_f32 v106, v168, 0x413504f3, v107
.LBB0_563:
	s_or_b64 exec, exec, s[48:49]
	s_and_b64 s[50:51], vcc, s[16:17]
	s_and_saveexec_b64 s[48:49], s[50:51]
	s_cbranch_execz .LBB0_565
	v_fmamk_f32 v89, v169, 0x413504f3, v91
.LBB0_565:
	s_or_b64 exec, exec, s[48:49]
	s_or_b64 s[48:49], s[18:19], s[36:37]
	s_nor_b64 s[50:51], s[48:49], s[20:21]
	v_mov_b32_e32 v90, 0xf149f2ca
	v_mov_b32_e32 v107, 0xf149f2ca
	s_and_saveexec_b64 s[48:49], s[50:51]
	s_cbranch_execz .LBB0_567
	v_fmamk_f32 v107, v170, 0x413504f3, v108
.LBB0_567:
	s_or_b64 exec, exec, s[48:49]
	s_nor_b64 s[50:51], s[36:37], s[22:23]
	s_and_saveexec_b64 s[48:49], s[50:51]
	s_cbranch_execz .LBB0_569
	v_fmamk_f32 v90, v171, 0x413504f3, v92
.LBB0_569:
	s_or_b64 exec, exec, s[48:49]
	s_or_b64 s[48:49], s[24:25], s[36:37]
	s_nor_b64 s[50:51], s[48:49], s[26:27]
	v_mov_b32_e32 v91, 0xf149f2ca
	v_mov_b32_e32 v108, 0xf149f2ca
	s_and_saveexec_b64 s[48:49], s[50:51]
	s_cbranch_execz .LBB0_571
	v_fmamk_f32 v108, v190, 0x413504f3, v109
.LBB0_571:
	s_or_b64 exec, exec, s[48:49]
	s_nor_b64 s[50:51], s[36:37], s[28:29]
	s_and_saveexec_b64 s[48:49], s[50:51]
	s_cbranch_execz .LBB0_573
	v_fmamk_f32 v91, v191, 0x413504f3, v93
.LBB0_573:
	s_or_b64 exec, exec, s[48:49]
	s_or_b64 s[48:49], s[30:31], s[36:37]
	s_nor_b64 s[50:51], s[48:49], s[34:35]
	v_mov_b32_e32 v92, 0xf149f2ca
	v_mov_b32_e32 v109, 0xf149f2ca
	s_and_saveexec_b64 s[48:49], s[50:51]
	s_cbranch_execz .LBB0_575
	v_fmamk_f32 v109, v193, 0x413504f3, v110
.LBB0_575:
	s_or_b64 exec, exec, s[48:49]
	s_nor_b64 s[50:51], s[36:37], s[42:43]
	s_and_saveexec_b64 s[48:49], s[50:51]
	s_cbranch_execz .LBB0_577
	v_fmamk_f32 v92, v194, 0x413504f3, v94
.LBB0_577:
	s_or_b64 exec, exec, s[48:49]
	s_or_b64 s[48:49], s[0:1], s[36:37]
	s_nor_b64 s[48:49], s[48:49], s[40:41]
	v_mov_b32_e32 v93, 0xf149f2ca
	v_mov_b32_e32 v94, 0xf149f2ca
	s_and_saveexec_b64 vcc, s[48:49]
	s_cbranch_execz .LBB0_579
	v_fmac_f32_e32 v111, 0x413504f3, v195
	v_mov_b32_e32 v94, v111
.LBB0_579:
	s_or_b64 exec, exec, vcc
	s_nor_b64 s[48:49], s[36:37], s[38:39]
	s_and_saveexec_b64 s[36:37], s[48:49]
	s_cbranch_execz .LBB0_581
	v_fmac_f32_e32 v95, 0x413504f3, v196
	v_mov_b32_e32 v93, v95

; #define SBAR() __builtin_amdgcn_sched_barrier(0)
; __device__ __forceinline__ void finishSM(f32x16& p0, f32x16& p1, float alpha, float& l_reg, bf16x8& pa0, bf16x8& pa1, bf16x8& pa2, bf16x8& pa3) {
; #pragma unroll
;   for (int r = 0; r < 16; ++r) p1[r] = __builtin_amdgcn_exp2f(p1[r]);
;   float ps = 0;
; #pragma unroll
;   for (int r = 0; r < 16; ++r) ps += p0[r];
; #pragma unroll
;   for (int r = 0; r < 16; ++r) ps += p1[r];
;   { auto rr = __builtin_amdgcn_permlane32_swap(__float_as_uint(ps), __float_as_uint(ps), false, false);
;     ps = __uint_as_float(rr[0]) + __uint_as_float(rr[1]); }
;   l_reg = l_reg * alpha + ps;
;     ...
;   PK4(p0, 0, pa0); PK4(p0, 8, pa1); PK4(p1, 0, pa2); PK4(p1, 8, pa3);
;     ...
; }
; template <int D0> __device__ __forceinline__ void pv_one(f32x16& od, int vb, bf16x8 pa0, bf16x8 pa1, bf16x8 pa2, bf16x8 pa3) {
;   const s16x4 l0 = tr_read<v_rd_off(D0, 0, 0)>(vb), h0 = tr_read<v_rd_off(D0, 0, 1)>(vb), l1 = tr_read<v_rd_off(D0, 1, 0)>(vb), h1 = tr_read<v_rd_off(D0, 1, 1)>(vb);
;   const s16x4 l2 = tr_read<v_rd_off(D0, 2, 0)>(vb), h2 = tr_read<v_rd_off(D0, 2, 1)>(vb), l3 = tr_read<v_rd_off(D0, 3, 0)>(vb), h3 = tr_read<v_rd_off(D0, 3, 1)>(vb);
;   asm volatile("s_waitcnt lgkmcnt(0)" ::: "memory"); SBAR();
;     ...
;   od = __builtin_amdgcn_mfma_f32_32x32x16_bf16(pa0, PK(l0, h0), od, 0, 0, 0);
;   od = __builtin_amdgcn_mfma_f32_32x32x16_bf16(pa1, PK(l1, h1), od, 0, 0, 0);
;   od = __builtin_amdgcn_mfma_f32_32x32x16_bf16(pa2, PK(l2, h2), od, 0, 0, 0);
;   od = __builtin_amdgcn_mfma_f32_32x32x16_bf16(pa3, PK(l3, h3), od, 0, 0, 0);
;     ...
; }
; __device__ __forceinline__ void pv_d0(f32x16* o, int vb, bf16x8 pa0, bf16x8 pa1, bf16x8 pa2, bf16x8 pa3) {
;   pv_one<0>(o[0], vb, pa0, pa1, pa2, pa3); pv_one<1>(o[1], vb, pa0, pa1, pa2, pa3); pv_one<2>(o[2], vb, pa0, pa1, pa2, pa3); pv_one<3>(o[3], vb, pa0, pa1, pa2, pa3);
.LBB0_655:
	v_cndmask_b32_e64 v3, v3, v237, s[0:1]
	v_mul_f32_e32 v3, 0xbe0293ee, v3
	v_fmamk_f32 v5, v7, 0x3e0293ee, v3
	v_fmamk_f32 v7, v9, 0x3e0293ee, v3
	v_exp_f32_e32 v82, v5
	v_fmamk_f32 v9, v11, 0x3e0293ee, v3
	v_exp_f32_e32 v84, v7
	v_fmamk_f32 v11, v13, 0x3e0293ee, v3
	v_fmamk_f32 v13, v15, 0x3e0293ee, v3
	v_fmamk_f32 v15, v97, 0x3e0293ee, v3
	v_fmamk_f32 v97, v99, 0x3e0293ee, v3
	v_exp_f32_e32 v80, v9
	v_fmamk_f32 v99, v101, 0x3e0293ee, v3
	v_fmamk_f32 v101, v103, 0x3e0293ee, v3
	v_fmamk_f32 v103, v112, 0x3e0293ee, v3
	v_fmamk_f32 v111, v114, 0x3e0293ee, v3
	v_fmamk_f32 v112, v116, 0x3e0293ee, v3
	v_fmamk_f32 v114, v117, 0x3e0293ee, v3
	v_fmamk_f32 v116, v118, 0x3e0293ee, v3
	v_fmamk_f32 v117, v119, 0x3e0293ee, v3
	v_fmamk_f32 v118, v120, 0x3e0293ee, v3
	v_fmamk_f32 v4, v6, 0x3e0293ee, v3
	v_fmamk_f32 v85, v8, 0x3e0293ee, v3
	v_fmamk_f32 v86, v10, 0x3e0293ee, v3
	v_fmamk_f32 v87, v12, 0x3e0293ee, v3
	v_fmamk_f32 v88, v14, 0x3e0293ee, v3
	v_fmamk_f32 v89, v96, 0x3e0293ee, v3
	v_fmamk_f32 v90, v98, 0x3e0293ee, v3
	v_fmamk_f32 v91, v100, 0x3e0293ee, v3
	v_fmamk_f32 v92, v102, 0x3e0293ee, v3
	v_fmamk_f32 v93, v104, 0x3e0293ee, v3
	v_fmamk_f32 v94, v113, 0x3e0293ee, v3
	v_fmamk_f32 v95, v115, 0x3e0293ee, v3
	v_fmamk_f32 v96, v107, 0x3e0293ee, v3
	v_exp_f32_e32 v83, v11
	v_exp_f32_e32 v14, v13
	v_exp_f32_e32 v13, v97
	v_fmamk_f32 v97, v108, 0x3e0293ee, v3
	v_fmamk_f32 v98, v109, 0x3e0293ee, v3
	v_fmac_f32_e32 v3, 0x3e0293ee, v110
	v_exp_f32_e32 v10, v101
	v_exp_f32_e32 v101, v3
	v_add_f32_e32 v3, 0, v82
	v_exp_f32_e32 v81, v15
	v_add_f32_e32 v3, v84, v3
	v_add_f32_e32 v3, v80, v3
	v_exp_f32_e32 v15, v99
	v_add_f32_e32 v3, v83, v3
	v_add_f32_e32 v3, v14, v3
	v_exp_f32_e32 v12, v103
	v_add_f32_e32 v3, v81, v3
	v_exp_f32_e32 v8, v111
	v_add_f32_e32 v3, v13, v3
	v_exp_f32_e32 v11, v112
	v_add_f32_e32 v3, v15, v3
	v_exp_f32_e32 v6, v114
	v_add_f32_e32 v3, v10, v3
	v_exp_f32_e32 v9, v116
	v_add_f32_e32 v3, v12, v3
	v_exp_f32_e32 v5, v117
	v_add_f32_e32 v3, v8, v3
	v_exp_f32_e32 v7, v118
	v_add_f32_e32 v3, v11, v3
	v_exp_f32_e32 v99, v4
	v_add_f32_e32 v3, v6, v3
	v_exp_f32_e32 v100, v85
	v_add_f32_e32 v3, v9, v3
	v_exp_f32_e32 v86, v86
	v_add_f32_e32 v3, v5, v3
	v_exp_f32_e32 v87, v87
	v_add_f32_e32 v3, v7, v3
	v_exp_f32_e32 v88, v88
	v_add_f32_e32 v3, v99, v3
	v_exp_f32_e32 v89, v89
	v_add_f32_e32 v3, v100, v3
	v_exp_f32_e32 v90, v90
	v_add_f32_e32 v3, v86, v3
	v_exp_f32_e32 v91, v91
	v_add_f32_e32 v3, v87, v3
	v_exp_f32_e32 v92, v92
	v_add_f32_e32 v3, v88, v3
	v_exp_f32_e32 v93, v93
	v_add_f32_e32 v3, v89, v3
	v_exp_f32_e32 v94, v94
	v_add_f32_e32 v3, v90, v3
	v_exp_f32_e32 v95, v95
	v_add_f32_e32 v3, v91, v3
	v_exp_f32_e32 v96, v96
	v_add_f32_e32 v3, v92, v3
	v_exp_f32_e32 v97, v97
	v_add_f32_e32 v3, v93, v3
	v_exp_f32_e32 v98, v98
	v_add_f32_e32 v3, v94, v3
	v_add_f32_e32 v3, v95, v3
	v_add_f32_e32 v3, v96, v3
	v_add_f32_e32 v3, v97, v3
	v_add_f32_e32 v3, v98, v3
	v_add_f32_e32 v3, v101, v3
	v_mov_b32_e32 v4, v3
	s_nop 1
	v_permlane32_swap_b32_e32 v3, v4
	v_cvt_pk_bf16_f32 v82, v82, v84
	v_cvt_pk_bf16_f32 v83, v80, v83
	v_cvt_pk_bf16_f32 v84, v14, v81
	v_cvt_pk_bf16_f32 v85, v13, v15
	v_cvt_pk_bf16_f32 v10, v10, v12
	v_cvt_pk_bf16_f32 v11, v8, v11
	v_cvt_pk_bf16_f32 v12, v6, v9
	v_cvt_pk_bf16_f32 v13, v5, v7
	v_cvt_pk_bf16_f32 v6, v99, v100
	v_cvt_pk_bf16_f32 v7, v86, v87
	v_cvt_pk_bf16_f32 v8, v88, v89
	v_cvt_pk_bf16_f32 v9, v90, v91
	v_cvt_pk_bf16_f32 v86, v92, v93
	v_cvt_pk_bf16_f32 v87, v94, v95
	v_cvt_pk_bf16_f32 v88, v96, v97
	v_cvt_pk_bf16_f32 v89, v98, v101
	s_nop 0
	v_permlane32_swap_b32_e32 v82, v84
	v_permlane32_swap_b32_e32 v83, v85
	v_permlane32_swap_b32_e32 v10, v12
	v_permlane32_swap_b32_e32 v11, v13
	v_permlane32_swap_b32_e32 v6, v8
	v_permlane32_swap_b32_e32 v7, v9
	v_permlane32_swap_b32_e32 v86, v88
	v_permlane32_swap_b32_e32 v87, v89
	ds_read_b64_tr_b16 v[90:91], v149 offset:0
	ds_read_b64_tr_b16 v[92:93], v149 offset:0x800
	ds_read_b64_tr_b16 v[94:95], v149 offset:0x1000
	ds_read_b64_tr_b16 v[96:97], v149 offset:0x1800
	ds_read_b64_tr_b16 v[98:99], v149 offset:0x2000
	ds_read_b64_tr_b16 v[100:101], v149 offset:0x2800
	ds_read_b64_tr_b16 v[108:109], v149 offset:0x3000
	ds_read_b64_tr_b16 v[110:111], v149 offset:0x3800
	s_waitcnt lgkmcnt(0)
	s_nop 0
	v_mfma_f32_32x32x16_bf16 v[32:47], v[82:85], v[90:93], v[32:47]
	ds_read_b64_tr_b16 v[90:91], v149 offset:0x200
	ds_read_b64_tr_b16 v[92:93], v149 offset:0xa00
	v_mfma_f32_32x32x16_bf16 v[32:47], v[10:13], v[94:97], v[32:47]
	ds_read_b64_tr_b16 v[94:95], v149 offset:0x1200
	ds_read_b64_tr_b16 v[96:97], v149 offset:0x1a00
	v_mfma_f32_32x32x16_bf16 v[32:47], v[6:9], v[98:101], v[32:47]
	ds_read_b64_tr_b16 v[98:99], v149 offset:0x2200
	ds_read_b64_tr_b16 v[100:101], v149 offset:0x2a00
	v_mfma_f32_32x32x16_bf16 v[32:47], v[86:89], v[108:111], v[32:47]
	ds_read_b64_tr_b16 v[108:109], v149 offset:0x3200
	ds_read_b64_tr_b16 v[110:111], v149 offset:0x3a00
	s_waitcnt lgkmcnt(0)
	v_mfma_f32_32x32x16_bf16 v[64:79], v[82:85], v[90:93], v[64:79]
	ds_read_b64_tr_b16 v[90:91], v149 offset:0x400
	ds_read_b64_tr_b16 v[92:93], v149 offset:0xc00
	v_mfma_f32_32x32x16_bf16 v[64:79], v[10:13], v[94:97], v[64:79]
	ds_read_b64_tr_b16 v[94:95], v149 offset:0x1400
	ds_read_b64_tr_b16 v[96:97], v149 offset:0x1c00
	v_mfma_f32_32x32x16_bf16 v[64:79], v[6:9], v[98:101], v[64:79]
	ds_read_b64_tr_b16 v[98:99], v149 offset:0x2400
	ds_read_b64_tr_b16 v[100:101], v149 offset:0x2c00
	v_mfma_f32_32x32x16_bf16 v[64:79], v[86:89], v[108:111], v[64:79]
	ds_read_b64_tr_b16 v[108:109], v149 offset:0x3400
	ds_read_b64_tr_b16 v[110:111], v149 offset:0x3c00
	s_waitcnt lgkmcnt(0)
; __device__ __forceinline__ int opaque_tid() { int t = threadIdx.x; asm volatile("" : "+v"(t)); return t; }
; __device__ __forceinline__ int crow(int r, int hi) { return (r & 3) + 8 * (r >> 2) + 4 * hi; }
; template <int DK, bool NA, bool QL, int SD> ...
;     ...
;   if (hi == 0) li_l[r32] = l_reg; asm volatile("s_waitcnt vmcnt(0) lgkmcnt(0)" ::: "memory");
; #pragma unroll
;   for (int r = 0; r < 16; ++r) { const float rl = __builtin_amdgcn_rcpf(li_l[crow(r, hi)]);
; #pragma unroll
;     for (int d = 0; d < 4; ++d) o[d][r] *= rl; }
; __device__ __forceinline__ void store_o_bf16(const att::f32x16 (&o)[4], bf16* base  , unsigned char* lds) {
;     const int tid = opaque_tid(), lane = tid & 63, wave = __builtin_amdgcn_readfirstlane(tid >> 6), r32 = lane & 31, hi = lane >> 5;
;     __syncthreads();
;     float* T = (float*)(lds + wave * 16896);
	v_mfma_f32_32x32x16_bf16 v[16:31], v[82:85], v[90:93], v[16:31]
	ds_read_b64_tr_b16 v[90:91], v149 offset:0x600
	ds_read_b64_tr_b16 v[92:93], v149 offset:0xe00
	v_mfma_f32_32x32x16_bf16 v[16:31], v[10:13], v[94:97], v[16:31]
	ds_read_b64_tr_b16 v[94:95], v149 offset:0x1600
	ds_read_b64_tr_b16 v[96:97], v149 offset:0x1e00
	v_mfma_f32_32x32x16_bf16 v[16:31], v[6:9], v[98:101], v[16:31]
	ds_read_b64_tr_b16 v[98:99], v149 offset:0x2600
	ds_read_b64_tr_b16 v[100:101], v149 offset:0x2e00
	v_mfma_f32_32x32x16_bf16 v[16:31], v[86:89], v[108:111], v[16:31]
	ds_read_b64_tr_b16 v[108:109], v149 offset:0x3600
	ds_read_b64_tr_b16 v[110:111], v149 offset:0x3e00
	s_waitcnt lgkmcnt(0)
	v_mfma_f32_32x32x16_bf16 v[48:63], v[82:85], v[90:93], v[48:63]
	v_mfma_f32_32x32x16_bf16 v[48:63], v[10:13], v[94:97], v[48:63]
	v_mfma_f32_32x32x16_bf16 v[48:63], v[6:9], v[98:101], v[48:63]
	v_mfma_f32_32x32x16_bf16 v[48:63], v[86:89], v[108:111], v[48:63]
	s_mov_b64 s[0:1], exec
	v_readlane_b32 s2, v255, 58
	v_readlane_b32 s3, v255, 59
	s_and_b64 s[2:3], s[0:1], s[2:3]
	s_mov_b64 exec, s[2:3]
	v_add_f32_e32 v5, v105, v106
	v_fmac_f32_e32 v5, v150, v0
	v_add_f32_e32 v0, v3, v4
	v_fmac_f32_e32 v0, v5, v2
	ds_write_b32 v148, v0
	s_or_b64 exec, exec, s[0:1]
	s_waitcnt vmcnt(0) lgkmcnt(0)
	ds_read_b128 v[2:5], v146
	ds_read_b128 v[6:9], v146 offset:32
	s_waitcnt lgkmcnt(1)
	v_rcp_f32_e32 v0, v2
	v_rcp_f32_e32 v2, v3
	v_rcp_f32_e32 v3, v4
	v_mul_f32_e32 v12, v0, v16
	v_mul_f32_e32 v13, v2, v33
	v_mul_f32_e32 v14, v2, v65
	v_mul_f32_e32 v15, v2, v17
	v_mul_f32_e32 v16, v2, v49
	v_rcp_f32_e32 v2, v5
	v_mul_f32_e32 v10, v0, v32
	v_mul_f32_e32 v11, v0, v64
	v_mul_f32_e32 v0, v0, v48
	v_mul_f32_e32 v17, v3, v34
	v_mul_f32_e32 v32, v3, v66
	v_mul_f32_e32 v18, v3, v18
	v_mul_f32_e32 v33, v3, v50
	v_mul_f32_e32 v34, v2, v35
	s_waitcnt lgkmcnt(0)
	v_rcp_f32_e32 v3, v6
	v_mul_f32_e32 v35, v2, v67
	v_mul_f32_e32 v19, v2, v19
	v_mul_f32_e32 v48, v2, v51
	v_rcp_f32_e32 v2, v7
	v_rcp_f32_e32 v6, v8
	v_mul_f32_e32 v36, v3, v36
	v_mul_f32_e32 v49, v3, v68
	v_mul_f32_e32 v20, v3, v20
	v_mul_f32_e32 v50, v3, v52
	v_mul_f32_e32 v37, v2, v37
	v_mul_f32_e32 v51, v2, v69
	v_mul_f32_e32 v21, v2, v21
	v_mul_f32_e32 v52, v2, v53
	v_mul_f32_e32 v38, v6, v38
	v_mul_f32_e32 v53, v6, v70
	v_rcp_f32_e32 v64, v9
	ds_read_b128 v[2:5], v146 offset:64
	v_mul_f32_e32 v22, v6, v22
	v_mul_f32_e32 v54, v6, v54
	ds_read_b128 v[6:9], v146 offset:96
	v_mul_f32_e32 v39, v64, v39
	s_waitcnt lgkmcnt(1)
	v_rcp_f32_e32 v2, v2
	v_rcp_f32_e32 v3, v3
	v_rcp_f32_e32 v4, v4
	v_rcp_f32_e32 v5, v5
	s_waitcnt lgkmcnt(0)
	v_rcp_f32_e32 v6, v6
	v_rcp_f32_e32 v7, v7
	v_rcp_f32_e32 v8, v8
	v_rcp_f32_e32 v9, v9
	v_mul_f32_e32 v65, v64, v71
	v_mul_f32_e32 v23, v64, v23
	v_mul_f32_e32 v55, v64, v55
	v_mul_f32_e32 v40, v2, v40
	v_mul_f32_e32 v64, v2, v72
	v_mul_f32_e32 v24, v2, v24
	v_mul_f32_e32 v2, v2, v56
	v_mul_f32_e32 v41, v3, v41
	v_mul_f32_e32 v56, v3, v73
	v_mul_f32_e32 v25, v3, v25
	v_mul_f32_e32 v3, v3, v57
	v_mul_f32_e32 v42, v4, v42
	v_mul_f32_e32 v57, v4, v74
	v_mul_f32_e32 v26, v4, v26
	v_mul_f32_e32 v4, v4, v58
	v_mul_f32_e32 v43, v5, v43
	v_mul_f32_e32 v58, v5, v75
	v_mul_f32_e32 v27, v5, v27
	v_mul_f32_e32 v5, v5, v59
	v_mul_f32_e32 v44, v6, v44
	v_mul_f32_e32 v59, v6, v76
	v_mul_f32_e32 v28, v6, v28
	v_mul_f32_e32 v6, v6, v60
	v_mul_f32_e32 v45, v7, v45
	v_mul_f32_e32 v60, v7, v77
	v_mul_f32_e32 v29, v7, v29
	v_mul_f32_e32 v7, v7, v61
	v_mul_f32_e32 v46, v8, v46
	v_mul_f32_e32 v61, v8, v78
	v_mul_f32_e32 v30, v8, v30
	v_mul_f32_e32 v8, v8, v62
	v_mul_f32_e32 v47, v9, v47
	v_mul_f32_e32 v62, v9, v79
	v_mul_f32_e32 v31, v9, v31
	v_mul_f32_e32 v9, v9, v63
	v_mov_b32_e32 v63, v188
	s_nop 0
	v_readfirstlane_b32 s0, v63
	s_ashr_i32 s2, s0, 6
	v_lshrrev_b32_e32 v67, 3, v63
	v_and_b32_e32 v66, 31, v63
	s_mul_i32 s0, s2, 0x4200
	v_and_b32_e32 v67, 4, v67
	s_add_i32 s0, s0, 0
	v_lshlrev_b32_e32 v66, 2, v66
	v_mul_u32_u24_e32 v67, 0x210, v67
	v_add3_u32 v66, s0, v66, v67
	s_barrier
; __device__ __forceinline__ int crow(int r, int hi) { return (r & 3) + 8 * (r >> 2) + 4 * hi; }
; __device__ __forceinline__ unsigned cvtpk(float lo, float hi) { unsigned r; asm volatile("v_cvt_pk_bf16_f32 %0, %1, %2" : "=v"(r) : "v"(lo), "v"(hi)); return r; }
; __device__ __forceinline__ void store_o_bf16(const att::f32x16 (&o)[4], bf16* base  , unsigned char* lds) {
;     ...
; #pragma unroll
;     for (int r = 0; r < 16; ++r) { float* tp = T + att::crow(r, hi) * 132 + r32;
; #pragma unroll
;         for (int d = 0; d < 4; ++d) tp[32 * d] = o[d][r]; }
; #pragma unroll
;     for (int k = 0; k < 8; ++k) { const int chunk = k * 64 + lane, row = chunk >> 4, c8 = chunk & 15;
;         const f32x4 a = *(const f32x4*)(T + row * 132 + c8 * 8), b = *(const f32x4*)(T + row * 132 + c8 * 8 + 4);
;         v4u w; w.x = att::cvtpk(a.x, a.y); w.y = att::cvtpk(a.z, a.w); w.z = att::cvtpk(b.x, b.y); w.w = att::cvtpk(b.z, b.w);
;         *(v4u*)(base + (size_t)(wave * 32 + row) * DM + c8 * 8) = w; }
	ds_write2_b32 v66, v10, v11 offset1:32
	ds_write2_b32 v66, v12, v0 offset0:64 offset1:96
	ds_write2_b32 v66, v13, v14 offset0:132 offset1:164
	ds_write2_b32 v66, v15, v16 offset0:196 offset1:228
	v_add_u32_e32 v0, 0x400, v66
	ds_write2_b32 v0, v17, v32 offset0:8 offset1:40
	ds_write2_b32 v0, v18, v33 offset0:72 offset1:104
	ds_write2_b32 v0, v34, v35 offset0:140 offset1:172
	ds_write2_b32 v0, v19, v48 offset0:204 offset1:236
	v_add_u32_e32 v0, 0x1000, v66
	ds_write2_b32 v0, v36, v49 offset0:32 offset1:64
	ds_write2_b32 v0, v20, v50 offset0:96 offset1:128
	ds_write2_b32 v0, v37, v51 offset0:164 offset1:196
	v_add_u32_e32 v0, 0x1200, v66
	ds_write2_b32 v0, v21, v52 offset0:100 offset1:132
	v_add_u32_e32 v0, 0x1400, v66
	ds_write2_b32 v0, v38, v53 offset0:40 offset1:72
	ds_write2_b32 v0, v22, v54 offset0:104 offset1:136
	ds_write2_b32 v0, v39, v65 offset0:172 offset1:204
	v_add_u32_e32 v0, 0x1600, v66
	ds_write2_b32 v0, v23, v55 offset0:108 offset1:140
	v_add_u32_e32 v0, 0x2000, v66
	ds_write2_b32 v0, v40, v64 offset0:64 offset1:96
	ds_write2_b32 v0, v24, v2 offset0:128 offset1:160
	ds_write2_b32 v0, v41, v56 offset0:196 offset1:228
	v_add_u32_e32 v0, 0x2400, v66
	ds_write2_b32 v0, v25, v3 offset0:4 offset1:36
	ds_write2_b32 v0, v42, v57 offset0:72 offset1:104
	ds_write2_b32 v0, v26, v4 offset0:136 offset1:168
	ds_write2_b32 v0, v43, v58 offset0:204 offset1:236
	v_add_u32_e32 v0, 0x2800, v66
	ds_write2_b32 v0, v27, v5 offset0:12 offset1:44
	v_add_u32_e32 v0, 0x3000, v66
	ds_write2_b32 v0, v44, v59 offset0:96 offset1:128
	ds_write2_b32 v0, v28, v6 offset0:160 offset1:192
	v_add_u32_e32 v0, 0x3200, v66
	ds_write2_b32 v0, v45, v60 offset0:100 offset1:132
	v_add_u32_e32 v0, 0x3400, v66
	ds_write2_b32 v0, v29, v7 offset0:36 offset1:68
	ds_write2_b32 v0, v46, v61 offset0:104 offset1:136
	ds_write2_b32 v0, v30, v8 offset0:168 offset1:200
	v_add_u32_e32 v0, 0x3600, v66
	ds_write2_b32 v0, v47, v62 offset0:108 offset1:140
	v_add_u32_e32 v0, 0x3800, v66
	ds_write2_b32 v0, v31, v9 offset0:44 offset1:76
	v_lshlrev_b32_e32 v0, 3, v63
	v_and_b32_e32 v0, 0x78, v0
	v_bfe_u32 v12, v63, 4, 2
	v_lshlrev_b32_e32 v2, 2, v0
	v_mul_u32_u24_e32 v3, 0x210, v12
	v_add3_u32 v22, s0, v2, v3
	v_readlane_b32 s0, v253, 7
	v_lshl_or_b32 v18, s2, 5, v12
	v_lshlrev_b32_e32 v0, 1, v0
	v_readlane_b32 s1, v253, 8
	v_ashrrev_i32_e32 v19, 31, v18
	ds_read_b128 v[2:5], v22
	ds_read_b128 v[8:11], v22 offset:16
	v_lshl_add_u64 v[16:17], s[0:1], 0, v[0:1]
	v_lshlrev_b64 v[20:21], 12, v[18:19]
	s_waitcnt lgkmcnt(1)
	v_cvt_pk_bf16_f32 v2, v2, v3
	v_cvt_pk_bf16_f32 v3, v4, v5
	s_waitcnt lgkmcnt(0)
	v_cvt_pk_bf16_f32 v4, v8, v9
	v_cvt_pk_bf16_f32 v5, v10, v11
	ds_read_b128 v[8:11], v22 offset:2112
	ds_read_b128 v[12:15], v22 offset:2128
	v_lshl_add_u64 v[20:21], v[16:17], 0, v[20:21]
	global_store_dwordx4 v[20:21], v[2:5], off offset:3072
	s_mov_b64 s[0:1], 0xc00
	v_lshl_add_u64 v[6:7], v[16:17], 0, s[0:1]
	s_waitcnt lgkmcnt(1)
	v_cvt_pk_bf16_f32 v2, v8, v9
	v_cvt_pk_bf16_f32 v3, v10, v11
	s_waitcnt lgkmcnt(0)
	v_cvt_pk_bf16_f32 v4, v12, v13
	v_or_b32_e32 v12, 4, v18
	v_ashrrev_i32_e32 v13, 31, v12
	v_lshlrev_b64 v[20:21], 12, v[12:13]
	v_cvt_pk_bf16_f32 v5, v14, v15
	ds_read_b128 v[8:11], v22 offset:4224
	ds_read_b128 v[12:15], v22 offset:4240
	v_lshl_add_u64 v[20:21], v[16:17], 0, v[20:21]
	global_store_dwordx4 v[20:21], v[2:5], off offset:3072
	s_mov_b64 s[0:1], 0
	s_waitcnt lgkmcnt(1)
	v_cvt_pk_bf16_f32 v2, v8, v9
	v_cvt_pk_bf16_f32 v3, v10, v11
	s_waitcnt lgkmcnt(0)
	v_cvt_pk_bf16_f32 v4, v12, v13
	v_or_b32_e32 v12, 8, v18
	v_ashrrev_i32_e32 v13, 31, v12
	v_lshlrev_b64 v[20:21], 12, v[12:13]
	v_cvt_pk_bf16_f32 v5, v14, v15
	ds_read_b128 v[8:11], v22 offset:6336
	ds_read_b128 v[12:15], v22 offset:6352
	v_lshl_add_u64 v[20:21], v[16:17], 0, v[20:21]
	global_store_dwordx4 v[20:21], v[2:5], off offset:3072
	s_waitcnt lgkmcnt(1)
	s_nop 0
	v_cvt_pk_bf16_f32 v2, v8, v9
	v_cvt_pk_bf16_f32 v3, v10, v11
	s_waitcnt lgkmcnt(0)
	v_cvt_pk_bf16_f32 v4, v12, v13
	v_or_b32_e32 v12, 12, v18
	v_ashrrev_i32_e32 v13, 31, v12
	v_lshlrev_b64 v[20:21], 12, v[12:13]
	v_cvt_pk_bf16_f32 v5, v14, v15
	ds_read_b128 v[8:11], v22 offset:8448
	ds_read_b128 v[12:15], v22 offset:8464
	v_lshl_add_u64 v[20:21], v[16:17], 0, v[20:21]
	global_store_dwordx4 v[20:21], v[2:5], off offset:3072
	s_waitcnt lgkmcnt(1)
	s_nop 0
	v_cvt_pk_bf16_f32 v2, v8, v9
	v_cvt_pk_bf16_f32 v3, v10, v11
	s_waitcnt lgkmcnt(0)
	v_cvt_pk_bf16_f32 v4, v12, v13
	v_or_b32_e32 v12, 16, v18
	v_ashrrev_i32_e32 v13, 31, v12
	v_lshlrev_b64 v[20:21], 12, v[12:13]
	v_cvt_pk_bf16_f32 v5, v14, v15
	ds_read_b128 v[8:11], v22 offset:10560
	ds_read_b128 v[12:15], v22 offset:10576
	v_lshl_add_u64 v[20:21], v[16:17], 0, v[20:21]
	global_store_dwordx4 v[20:21], v[2:5], off offset:3072
	s_waitcnt lgkmcnt(1)
	s_nop 0
	v_cvt_pk_bf16_f32 v2, v8, v9
	v_cvt_pk_bf16_f32 v3, v10, v11
	s_waitcnt lgkmcnt(0)
	v_cvt_pk_bf16_f32 v4, v12, v13
	v_or_b32_e32 v12, 20, v18
	v_ashrrev_i32_e32 v13, 31, v12
	v_lshlrev_b64 v[20:21], 12, v[12:13]
	v_cvt_pk_bf16_f32 v5, v14, v15
	ds_read_b128 v[8:11], v22 offset:12672
	ds_read_b128 v[12:15], v22 offset:12688
	v_lshl_add_u64 v[20:21], v[16:17], 0, v[20:21]
	global_store_dwordx4 v[20:21], v[2:5], off offset:3072
	s_waitcnt lgkmcnt(1)
	s_nop 0
	v_cvt_pk_bf16_f32 v2, v8, v9
	v_cvt_pk_bf16_f32 v3, v10, v11
	s_waitcnt lgkmcnt(0)
	v_cvt_pk_bf16_f32 v4, v12, v13
	v_or_b32_e32 v12, 24, v18
	v_ashrrev_i32_e32 v13, 31, v12
	v_lshlrev_b64 v[20:21], 12, v[12:13]
	v_cvt_pk_bf16_f32 v5, v14, v15
	ds_read_b128 v[8:11], v22 offset:14784
	ds_read_b128 v[12:15], v22 offset:14800
	v_lshl_add_u64 v[16:17], v[16:17], 0, v[20:21]
	global_store_dwordx4 v[16:17], v[2:5], off offset:3072
	s_waitcnt lgkmcnt(1)
	s_nop 0
	v_cvt_pk_bf16_f32 v2, v8, v9
	v_cvt_pk_bf16_f32 v3, v10, v11
	s_waitcnt lgkmcnt(0)
	v_cvt_pk_bf16_f32 v4, v12, v13
	v_cvt_pk_bf16_f32 v5, v14, v15
	v_or_b32_e32 v8, 28, v18
	v_mov_b64_e32 v[168:169], 0x100
	v_mov_b64_e32 v[170:171], 0xff
	v_mov_b32_e32 v190, 0x260
	v_mov_b32_e32 v191, 1
	v_mov_b32_e32 v193, 0x3a83126f
	v_mov_b32_e32 v194, 0x3c23d70a
	v_mov_b32_e32 v195, 0x2800
	v_mov_b64_e32 v[196:197], 0x580
